# LayerNorm phase: nt cache hint on the streamed residual loads and f32 output stores
# speedup vs baseline: 1.0180x; 1.0180x over previous
; DI void ln_phase(const Args& a, int l) {
;     ...
;     for (int gw = blockIdx.x * 8 + wid; gw < TL / 16; gw += gridDim.x * 8) {
;         const int bb = gw >> 8;
; #pragma unroll
;         for (int i = 0; i < 4; ++i) { const int col = 4 * lane + 256 * i; gate[i] = *(const f32x4*)(modl + bb * 3072 + 2048 + col);
;             sh[i] = *(const f32x4*)(modn + bb * 3072 + col); sc1[i] = *(const f32x4*)(modn + bb * 3072 + 1024 + col) + 1.f; }
; #pragma unroll 1
;         for (int r0 = 0; r0 < 15; r0 += 3) ln_rows<3>(a, l, gw * 16 + r0, lane, lgv, lbv, gate, sh, sc1);
.LBB0_973:
	v_lshrrev_b32_e32 v32, 8, v211
	v_mul_i32_i24_e32 v32, 0xc00, v32
	v_ashrrev_i32_e32 v33, 31, v32
	v_lshlrev_b64 v[32:33], 2, v[32:33]
	v_lshl_add_u64 v[34:35], s[10:11], 0, v[32:33]
	s_mov_b64 s[0:1], 0x2000
	v_lshl_add_u64 v[34:35], v[34:35], 0, s[0:1]
	v_lshl_add_u64 v[32:33], s[14:15], 0, v[32:33]
	s_mov_b64 s[0:1], 0x1000
	v_lshl_add_u64 v[36:37], v[32:33], 0, s[0:1]
	v_lshl_add_u64 v[38:39], v[34:35], 0, v[180:181]
	v_lshl_add_u64 v[32:33], v[32:33], 0, v[180:181]
	global_load_dwordx4 v[60:63], v[38:39], off nt
	global_load_dwordx4 v[40:43], v[32:33], off nt
	v_lshl_add_u64 v[38:39], v[36:37], 0, v[180:181]
	v_mov_b32_e32 v103, v181
	global_load_dwordx4 v[64:67], v[38:39], off nt
	v_lshl_add_u64 v[38:39], v[34:35], 0, v[102:103]
	v_mov_b32_e32 v105, v181
	v_lshl_add_u64 v[44:45], v[36:37], 0, v[102:103]
	global_load_dwordx4 v[56:59], v[38:39], off nt
	global_load_dwordx4 v[68:71], v[44:45], off nt
	v_lshl_add_u64 v[38:39], v[34:35], 0, v[104:105]
	v_lshl_add_u64 v[44:45], v[36:37], 0, v[104:105]
	global_load_dwordx4 v[52:55], v[38:39], off nt
	global_load_dwordx4 v[72:75], v[44:45], off nt
	v_mov_b32_e32 v107, v181
	v_lshl_add_u64 v[34:35], v[34:35], 0, v[106:107]
	v_lshl_add_u64 v[36:37], v[36:37], 0, v[106:107]
	global_load_dwordx4 v[48:51], v[34:35], off nt
	global_load_dwordx4 v[76:79], v[36:37], off nt
	global_load_dwordx4 v[44:47], v[32:33], off offset:1024 nt
	s_nop 0
	global_load_dwordx4 v[36:39], v[32:33], off offset:2048 nt
	s_nop 0
	global_load_dwordx4 v[32:35], v[32:33], off offset:3072 nt
	v_ashrrev_i32_e32 v95, 31, v94
	v_lshlrev_b64 v[80:81], 11, v[94:95]
	v_lshlrev_b64 v[82:83], 12, v[94:95]
	v_lshl_add_u64 v[124:125], v[96:97], 0, v[80:81]
	v_lshl_add_u64 v[126:127], v[98:99], 0, v[82:83]
	v_lshl_add_u64 v[128:129], v[100:101], 0, v[82:83]
	s_mov_b32 s69, -3
	s_waitcnt vmcnt(9)
	v_pk_add_f32 v[122:123], v[66:67], 1.0 op_sel_hi:[1,0]
	v_pk_add_f32 v[120:121], v[64:65], 1.0 op_sel_hi:[1,0]
	s_waitcnt vmcnt(7)
	v_pk_add_f32 v[118:119], v[70:71], 1.0 op_sel_hi:[1,0]
	v_pk_add_f32 v[116:117], v[68:69], 1.0 op_sel_hi:[1,0]
	s_waitcnt vmcnt(5)
	v_pk_add_f32 v[114:115], v[74:75], 1.0 op_sel_hi:[1,0]
	v_pk_add_f32 v[112:113], v[72:73], 1.0 op_sel_hi:[1,0]
	s_waitcnt vmcnt(3)
	v_pk_add_f32 v[110:111], v[78:79], 1.0 op_sel_hi:[1,0]
	v_pk_add_f32 v[108:109], v[76:77], 1.0 op_sel_hi:[1,0]
	s_branch .LBB0_975

; DI float bflo(unsigned w) { return __uint_as_float(w << 16); }
; DI float bfhi(unsigned w) { return __uint_as_float(w & 0xffff0000u); }
; template <int NR>
; DI void ln_rows(const Args& a, int l, int row0, int lane, const f32x4 (&lgv)[4], const f32x4 (&lbv)[4], const f32x4 (&gate)[4], const f32x4 (&sh)[4], const f32x4 (&sc1)[4]) {
;     ...
;     for (int k = 0; k < NR; ++k) { const int row = row0 + k; s[k] = 0.f;
;         const float* xr = row < TL ? xlat + (size_t)row * 1024 : xctx + (size_t)(row - TL) * 1024;
; #pragma unroll
;         for (int i = 0; i < 4; ++i) { const int col = 4 * lane + 256 * i;
;             const f32x4 xv = *(const f32x4*)(xr + col); const u32x2 yw = *(const u32x2*)(y + (size_t)row * 1024 + col);
;             f32x4 yv; yv[0] = bflo(yw[0]); yv[1] = bfhi(yw[0]); yv[2] = bflo(yw[1]); yv[3] = bfhi(yw[1]);
;             v[k][i] = xv * ALPHA + gate[i] * yv; s[k] += v[k][i][0] + v[k][i][1] + v[k][i][2] + v[k][i][3]; } }
.LBB0_975:
	global_load_dwordx2 v[138:139], v[124:125], off
	global_load_dwordx2 v[140:141], v[124:125], off offset:512
	global_load_dwordx2 v[142:143], v[124:125], off offset:1024
	global_load_dwordx2 v[144:145], v[124:125], off offset:1536
	global_load_dwordx4 v[76:79], v[126:127], off offset:-2048 nt
	global_load_dwordx4 v[72:75], v[126:127], off offset:-1024 nt
	global_load_dwordx4 v[68:71], v[126:127], off nt
	global_load_dwordx4 v[64:67], v[126:127], off offset:1024 nt
	v_add_u32_e32 v81, s69, v94
	v_add_u32_e32 v80, 4, v81
	v_add_u32_e32 v103, 3, v81
	v_add_u32_e32 v82, 5, v81
	v_ashrrev_i32_e32 v81, 31, v80
	v_lshlrev_b64 v[136:137], 11, v[80:81]
	v_lshl_add_u64 v[150:151], v[90:91], 0, v[136:137]
	global_load_dwordx2 v[152:153], v[150:151], off
	v_lshlrev_b64 v[134:135], 12, v[80:81]
	v_lshl_add_u64 v[80:81], v[86:87], 0, v[134:135]
	global_load_dwordx4 v[146:149], v[80:81], off nt
	v_ashrrev_i32_e32 v83, 31, v82
	v_lshlrev_b64 v[132:133], 12, v[82:83]
	v_lshlrev_b64 v[130:131], 11, v[82:83]
	global_load_dwordx2 v[188:189], v[150:151], off offset:512
	global_load_dwordx4 v[156:159], v[80:81], off offset:1024 nt
	global_load_dwordx4 v[170:173], v[80:81], off offset:2048 nt
	s_nop 0
	global_load_dwordx4 v[80:83], v[80:81], off offset:3072 nt
	s_nop 0
	global_load_dwordx2 v[190:191], v[150:151], off offset:1024
	global_load_dwordx2 v[192:193], v[150:151], off offset:1536
	s_movk_i32 s0, 0x7ffe
	v_mov_b32_e32 v89, s21
	v_mov_b32_e32 v95, s20
	v_lshl_add_u64 v[154:155], s[18:19], 0, v[132:133]
	v_cmp_gt_i32_e64 s[6:7], s0, v103
	v_lshl_add_u64 v[160:161], v[90:91], 0, v[130:131]
	global_load_dwordx2 v[194:195], v[160:161], off
	global_load_dwordx2 v[196:197], v[160:161], off offset:512
	v_cndmask_b32_e64 v151, v89, v155, s[6:7]
	v_cndmask_b32_e64 v150, v95, v154, s[6:7]
	v_lshl_add_u64 v[198:199], v[150:151], 0, v[180:181]
	global_load_dwordx4 v[184:187], v[198:199], off nt
	s_mov_b64 s[8:9], -1
	s_waitcnt vmcnt(18)
	v_lshlrev_b32_e32 v150, 16, v138
	v_and_b32_e32 v151, 0xffff0000, v138
	s_waitcnt vmcnt(17)
	v_lshlrev_b32_e32 v154, 16, v140
	v_and_b32_e32 v155, 0xffff0000, v140
	v_lshlrev_b32_e32 v138, 16, v139
	v_and_b32_e32 v139, 0xffff0000, v139
	v_lshlrev_b32_e32 v140, 16, v141
	v_and_b32_e32 v141, 0xffff0000, v141
	s_waitcnt vmcnt(16)
	v_lshlrev_b32_e32 v162, 16, v142
	v_and_b32_e32 v163, 0xffff0000, v142
	s_waitcnt vmcnt(15)
	v_lshlrev_b32_e32 v164, 16, v144
	v_and_b32_e32 v165, 0xffff0000, v144
	v_lshlrev_b32_e32 v144, 16, v145
	v_and_b32_e32 v145, 0xffff0000, v145
	v_pk_mul_f32 v[150:151], v[60:61], v[150:151]
	v_pk_mul_f32 v[154:155], v[56:57], v[154:155]
	v_pk_mul_f32 v[138:139], v[62:63], v[138:139]
	v_pk_mul_f32 v[140:141], v[58:59], v[140:141]
	v_pk_mul_f32 v[162:163], v[52:53], v[162:163]
	v_pk_mul_f32 v[200:201], v[48:49], v[164:165]
	v_pk_mul_f32 v[144:145], v[50:51], v[144:145]
	s_waitcnt vmcnt(14)
	v_pk_fma_f32 v[178:179], v[76:77], s[44:45], v[150:151] op_sel_hi:[1,0,1]
	s_waitcnt vmcnt(13)
	v_pk_fma_f32 v[174:175], v[72:73], s[44:45], v[154:155] op_sel_hi:[1,0,1]
	v_lshlrev_b32_e32 v142, 16, v143
	v_and_b32_e32 v143, 0xffff0000, v143
	v_pk_fma_f32 v[176:177], v[78:79], s[44:45], v[138:139] op_sel_hi:[1,0,1]
	v_pk_fma_f32 v[168:169], v[74:75], s[44:45], v[140:141] op_sel_hi:[1,0,1]
	s_waitcnt vmcnt(12)
	v_pk_fma_f32 v[166:167], v[68:69], s[44:45], v[162:163] op_sel_hi:[1,0,1]
	s_waitcnt vmcnt(11)
	v_pk_fma_f32 v[154:155], v[66:67], s[44:45], v[144:145] op_sel_hi:[1,0,1]
	v_pk_fma_f32 v[162:163], v[64:65], s[44:45], v[200:201] op_sel_hi:[1,0,1]
	v_mov_b32_e32 v64, v178
	v_mov_b32_e32 v65, v174
	v_mov_b32_e32 v66, v179
	v_mov_b32_e32 v67, v175
	v_pk_mul_f32 v[142:143], v[54:55], v[142:143]
	v_mov_b32_e32 v68, v176
	v_mov_b32_e32 v69, v168
	v_pk_add_f32 v[64:65], v[64:65], v[66:67]
	v_pk_fma_f32 v[164:165], v[70:71], s[44:45], v[142:143] op_sel_hi:[1,0,1]
	v_mov_b32_e32 v70, v177
	v_mov_b32_e32 v71, v169
	v_pk_add_f32 v[64:65], v[68:69], v[64:65]
	v_mov_b32_e32 v72, v166
	v_pk_add_f32 v[64:65], v[70:71], v[64:65]
	v_mov_b32_e32 v73, v162
	v_mov_b32_e32 v74, v167
	v_mov_b32_e32 v75, v163
	v_add_f32_e32 v64, 0, v64
	v_pk_add_f32 v[66:67], v[72:73], v[74:75]
	v_add_f32_e32 v72, v64, v65
	v_mov_b32_e32 v64, v164
	v_mov_b32_e32 v65, v154
	v_pk_add_f32 v[68:69], v[64:65], v[66:67]
	v_mov_b32_e32 v70, v165
	v_mov_b32_e32 v71, v155
	global_load_dwordx4 v[64:67], v[198:199], off offset:1024 nt
	v_pk_add_f32 v[68:69], v[70:71], v[68:69]
	s_waitcnt vmcnt(11)
	v_lshlrev_b32_e32 v70, 16, v153
	v_add_f32_e32 v68, v72, v68
	v_add_f32_e32 v89, v68, v69
	v_lshlrev_b32_e32 v68, 16, v152
	v_and_b32_e32 v69, 0xffff0000, v152
	v_and_b32_e32 v71, 0xffff0000, v153
	v_pk_mul_f32 v[68:69], v[60:61], v[68:69]
	v_pk_mul_f32 v[70:71], v[62:63], v[70:71]
	s_waitcnt vmcnt(10)
	v_pk_fma_f32 v[152:153], v[146:147], s[44:45], v[68:69] op_sel_hi:[1,0,1]
	v_pk_fma_f32 v[150:151], v[148:149], s[44:45], v[70:71] op_sel_hi:[1,0,1]
	s_waitcnt vmcnt(9)
	v_lshlrev_b32_e32 v68, 16, v188
	v_and_b32_e32 v69, 0xffff0000, v188
	v_lshlrev_b32_e32 v70, 16, v189
	global_load_dwordx2 v[74:75], v[160:161], off offset:1024
	global_load_dwordx2 v[76:77], v[160:161], off offset:1536
	v_and_b32_e32 v71, 0xffff0000, v189
	v_pk_mul_f32 v[68:69], v[56:57], v[68:69]
	v_pk_mul_f32 v[70:71], v[58:59], v[70:71]
	s_waitcnt vmcnt(10)
	v_pk_fma_f32 v[156:157], v[156:157], s[44:45], v[68:69] op_sel_hi:[1,0,1]
	v_pk_fma_f32 v[140:141], v[158:159], s[44:45], v[70:71] op_sel_hi:[1,0,1]
	global_load_dwordx4 v[68:71], v[198:199], off offset:2048 nt
	global_load_dwordx4 v[158:161], v[198:199], off offset:3072 nt
	v_mov_b32_e32 v72, v152
	v_mov_b32_e32 v73, v156
	v_mov_b32_e32 v78, v153
	v_mov_b32_e32 v79, v157
	v_pk_add_f32 v[72:73], v[72:73], v[78:79]
	v_mov_b32_e32 v78, v150
	v_mov_b32_e32 v79, v140
	v_pk_add_f32 v[72:73], v[78:79], v[72:73]
	v_mov_b32_e32 v78, v151
	v_mov_b32_e32 v79, v141
	v_pk_add_f32 v[72:73], v[78:79], v[72:73]
	s_waitcnt vmcnt(9)
; DI float bflo(unsigned w) { return __uint_as_float(w << 16); }
; DI float bfhi(unsigned w) { return __uint_as_float(w & 0xffff0000u); }
; template <int NR>
; DI void ln_rows(const Args& a, int l, int row0, int lane, const f32x4 (&lgv)[4], const f32x4 (&lbv)[4], const f32x4 (&gate)[4], const f32x4 (&sh)[4], const f32x4 (&sc1)[4]) {
;     ...
;         for (int i = 0; i < 4; ++i) { const int col = 4 * lane + 256 * i;
;             const f32x4 xv = *(const f32x4*)(xr + col); const u32x2 yw = *(const u32x2*)(y + (size_t)row * 1024 + col);
;             f32x4 yv; yv[0] = bflo(yw[0]); yv[1] = bfhi(yw[0]); yv[2] = bflo(yw[1]); yv[3] = bfhi(yw[1]);
;             v[k][i] = xv * ALPHA + gate[i] * yv; s[k] += v[k][i][0] + v[k][i][1] + v[k][i][2] + v[k][i][3]; } }
;     float mean[NR], rstd[NR];
; #pragma unroll
;     for (int k = 0; k < NR; ++k) mean[k] = wave_sum(s[k]) * (1.f / 1024.f);
	v_lshlrev_b32_e32 v78, 16, v191
	v_add_f32_e32 v72, 0, v72
	v_add_f32_e32 v95, v72, v73
	v_lshlrev_b32_e32 v72, 16, v190
	v_and_b32_e32 v73, 0xffff0000, v190
	v_and_b32_e32 v79, 0xffff0000, v191
	v_pk_mul_f32 v[72:73], v[52:53], v[72:73]
	v_pk_mul_f32 v[78:79], v[54:55], v[78:79]
	v_pk_fma_f32 v[148:149], v[170:171], s[44:45], v[72:73] op_sel_hi:[1,0,1]
	s_waitcnt vmcnt(8)
	v_lshlrev_b32_e32 v72, 16, v192
	v_and_b32_e32 v73, 0xffff0000, v192
	v_pk_fma_f32 v[146:147], v[172:173], s[44:45], v[78:79] op_sel_hi:[1,0,1]
	v_lshlrev_b32_e32 v78, 16, v193
	v_and_b32_e32 v79, 0xffff0000, v193
	v_pk_mul_f32 v[72:73], v[48:49], v[72:73]
	v_pk_mul_f32 v[78:79], v[50:51], v[78:79]
	v_pk_fma_f32 v[142:143], v[80:81], s[44:45], v[72:73] op_sel_hi:[1,0,1]
	v_pk_fma_f32 v[138:139], v[82:83], s[44:45], v[78:79] op_sel_hi:[1,0,1]
	v_mov_b32_e32 v72, v148
	v_mov_b32_e32 v73, v142
	v_mov_b32_e32 v78, v149
	v_mov_b32_e32 v79, v143
	v_pk_add_f32 v[72:73], v[72:73], v[78:79]
	v_mov_b32_e32 v78, v146
	v_mov_b32_e32 v79, v138
	v_pk_add_f32 v[72:73], v[78:79], v[72:73]
	v_mov_b32_e32 v78, v147
	v_mov_b32_e32 v79, v139
	v_pk_add_f32 v[72:73], v[78:79], v[72:73]
	s_waitcnt vmcnt(7)
	v_lshlrev_b32_e32 v78, 16, v195
	v_add_f32_e32 v72, v95, v72
	v_add_f32_e32 v95, v72, v73
	v_lshlrev_b32_e32 v72, 16, v194
	v_and_b32_e32 v73, 0xffff0000, v194
	v_and_b32_e32 v79, 0xffff0000, v195
	v_pk_mul_f32 v[72:73], v[60:61], v[72:73]
	v_pk_mul_f32 v[78:79], v[62:63], v[78:79]
	s_waitcnt vmcnt(5)
	v_pk_fma_f32 v[82:83], v[184:185], s[44:45], v[72:73] op_sel_hi:[1,0,1]
	v_lshlrev_b32_e32 v72, 16, v196
	v_and_b32_e32 v73, 0xffff0000, v196
	v_pk_fma_f32 v[80:81], v[186:187], s[44:45], v[78:79] op_sel_hi:[1,0,1]
	v_lshlrev_b32_e32 v78, 16, v197
	v_and_b32_e32 v79, 0xffff0000, v197
	v_pk_mul_f32 v[144:145], v[56:57], v[72:73]
	v_pk_mul_f32 v[72:73], v[58:59], v[78:79]
	s_waitcnt vmcnt(4)
	v_pk_fma_f32 v[78:79], v[64:65], s[44:45], v[144:145] op_sel_hi:[1,0,1]
	v_pk_fma_f32 v[72:73], v[66:67], s[44:45], v[72:73] op_sel_hi:[1,0,1]
	v_mov_b32_e32 v64, v82
	v_mov_b32_e32 v65, v78
	v_mov_b32_e32 v66, v83
	v_mov_b32_e32 v67, v79
	v_pk_add_f32 v[64:65], v[64:65], v[66:67]
	v_mov_b32_e32 v66, v80
	v_mov_b32_e32 v67, v72
	v_pk_add_f32 v[64:65], v[66:67], v[64:65]
	v_mov_b32_e32 v66, v81
	v_mov_b32_e32 v67, v73
	v_pk_add_f32 v[64:65], v[66:67], v[64:65]
	s_waitcnt vmcnt(3)
	v_lshlrev_b32_e32 v66, 16, v75
	v_and_b32_e32 v67, 0xffff0000, v75
	v_add_f32_e32 v64, 0, v64
	v_pk_mul_f32 v[66:67], v[54:55], v[66:67]
	v_add_f32_e32 v103, v64, v65
	v_lshlrev_b32_e32 v64, 16, v74
	v_and_b32_e32 v65, 0xffff0000, v74
	s_waitcnt vmcnt(1)
	v_pk_fma_f32 v[70:71], v[70:71], s[44:45], v[66:67] op_sel_hi:[1,0,1]
	v_lshlrev_b32_e32 v66, 16, v77
	v_and_b32_e32 v67, 0xffff0000, v77
	v_pk_mul_f32 v[64:65], v[52:53], v[64:65]
	v_pk_mul_f32 v[66:67], v[50:51], v[66:67]
	v_pk_fma_f32 v[74:75], v[68:69], s[44:45], v[64:65] op_sel_hi:[1,0,1]
	s_waitcnt vmcnt(0)
	v_pk_fma_f32 v[68:69], v[160:161], s[44:45], v[66:67] op_sel_hi:[1,0,1]
	v_mov_b32_e32 v67, v89
	v_mov_b32_e32 v212, v89
	s_mov_b32 s100, 0
	s_mov_b32 s101, -1
	v_permlane32_swap_b32_e32 v67, v212
	v_cndmask_b32_e64 v67, v212, v67, s[100:101]
	v_lshlrev_b32_e32 v64, 16, v76
	v_and_b32_e32 v65, 0xffff0000, v76
	v_pk_mul_f32 v[64:65], v[48:49], v[64:65]
	v_mov_b32_e32 v66, v75
	s_waitcnt lgkmcnt(0)
	v_add_f32_e32 v89, v89, v67
	v_mov_b32_e32 v105, v89
	v_mov_b32_e32 v212, v89
	s_mov_b32 s100, 0xffff0000
	s_mov_b32 s101, 0xffff0000
	v_permlane16_swap_b32_e32 v105, v212
	v_cndmask_b32_e64 v105, v212, v105, s[100:101]
	v_pk_fma_f32 v[76:77], v[158:159], s[44:45], v[64:65] op_sel_hi:[1,0,1]
	v_mov_b32_e32 v64, v74
	v_mov_b32_e32 v65, v76
	v_mov_b32_e32 v67, v77
	s_waitcnt lgkmcnt(0)
	v_add_f32_e32 v89, v89, v105
	s_nop 1
	v_mov_b32_dpp v105, v89 row_ror:8 row_mask:0xf bank_mask:0xf
	v_pk_add_f32 v[64:65], v[64:65], v[66:67]
	v_mov_b32_e32 v66, v70
	v_mov_b32_e32 v67, v68
	v_pk_add_f32 v[64:65], v[66:67], v[64:65]
	v_mov_b32_e32 v66, v71
	v_mov_b32_e32 v67, v69
	v_pk_add_f32 v[64:65], v[66:67], v[64:65]
	s_waitcnt lgkmcnt(0)
	v_add_f32_e32 v66, v89, v105
	s_nop 1
	v_mov_b32_dpp v67, v66 row_ror:4 row_mask:0xf bank_mask:0xf
	v_add_f32_e32 v64, v103, v64
	v_add_f32_e32 v64, v64, v65
	v_mov_b32_e32 v65, v64
	v_mov_b32_e32 v212, v64
	s_mov_b32 s100, 0
	s_mov_b32 s101, -1
	v_permlane32_swap_b32_e32 v65, v212
	v_cndmask_b32_e64 v65, v212, v65, s[100:101]
	v_mov_b32_e32 v89, v95
	v_mov_b32_e32 v212, v95
	s_mov_b32 s100, 0
	s_mov_b32 s101, -1
	v_permlane32_swap_b32_e32 v89, v212
	v_cndmask_b32_e64 v89, v212, v89, s[100:101]
	s_waitcnt lgkmcnt(2)
	v_add_f32_e32 v66, v66, v67
	s_nop 1
	v_mov_b32_dpp v67, v66 quad_perm:[2,3,0,1] row_mask:0xf bank_mask:0xf
	s_waitcnt lgkmcnt(2)
	v_add_f32_e32 v64, v64, v65
	v_mov_b32_e32 v65, v64
	v_mov_b32_e32 v212, v64
	s_mov_b32 s100, 0xffff0000
	s_mov_b32 s101, 0xffff0000
	v_permlane16_swap_b32_e32 v65, v212
	v_cndmask_b32_e64 v65, v212, v65, s[100:101]
	s_waitcnt lgkmcnt(2)
	v_add_f32_e32 v89, v95, v89
	s_waitcnt lgkmcnt(1)
	v_add_f32_e32 v66, v66, v67
	s_nop 1
	v_mov_b32_dpp v67, v66 quad_perm:[1,0,3,2] row_mask:0xf bank_mask:0xf
	v_mov_b32_e32 v95, v89
	v_mov_b32_e32 v212, v89
	s_mov_b32 s100, 0xffff0000
	s_mov_b32 s101, 0xffff0000
	v_permlane16_swap_b32_e32 v95, v212
	v_cndmask_b32_e64 v95, v212, v95, s[100:101]
	s_waitcnt lgkmcnt(2)
	v_add_f32_e32 v64, v64, v65
	s_nop 1
	v_mov_b32_dpp v65, v64 row_ror:8 row_mask:0xf bank_mask:0xf
	s_waitcnt lgkmcnt(2)
	v_add_f32_e32 v103, v66, v67
	s_waitcnt lgkmcnt(1)
; template <int NR>
; DI void ln_rows(const Args& a, int l, int row0, int lane, const f32x4 (&lgv)[4], const f32x4 (&lbv)[4], const f32x4 (&gate)[4], const f32x4 (&sh)[4], const f32x4 (&sc1)[4]) {
;     ...
;     for (int k = 0; k < NR; ++k) mean[k] = wave_sum(s[k]) * (1.f / 1024.f);
; #pragma unroll
;     for (int k = 0; k < NR; ++k) { float q = 0.f;
; #pragma unroll
;         for (int i = 0; i < 4; ++i) { v[k][i] = v[k][i] - mean[k]; q += v[k][i][0] * v[k][i][0] + v[k][i][1] * v[k][i][1] + v[k][i][2] * v[k][i][2] + v[k][i][3] * v[k][i][3]; }
;         rstd[k] = rsqrtf(wave_sum(q) * (1.f / 1024.f) + 1e-5f); }
	v_add_f32_e32 v89, v89, v95
	v_fmamk_f32 v179, v103, 0xba800000, v179
	v_fmamk_f32 v175, v103, 0xba800000, v175
	s_nop 1
	v_mov_b32_dpp v95, v89 row_ror:8 row_mask:0xf bank_mask:0xf
	v_fmac_f32_e32 v178, 0xba800000, v103
	v_fmac_f32_e32 v174, 0xba800000, v103
	v_mov_b32_e32 v66, v179
	v_mov_b32_e32 v67, v175
	s_waitcnt lgkmcnt(1)
	v_add_f32_e32 v105, v64, v65
	v_fmac_f32_e32 v176, 0xba800000, v103
	v_fmac_f32_e32 v168, 0xba800000, v103
	v_mov_b32_e32 v64, v178
	v_mov_b32_e32 v65, v174
	v_pk_mul_f32 v[66:67], v[66:67], v[66:67]
	v_fmamk_f32 v195, v103, 0xba800000, v167
	v_pk_fma_f32 v[64:65], v[64:65], v[64:65], v[66:67]
	v_mov_b32_e32 v66, v176
	v_mov_b32_e32 v67, v168
	v_fmac_f32_e32 v166, 0xba800000, v103
	v_fmamk_f32 v194, v103, 0xba800000, v163
	v_fmamk_f32 v177, v103, 0xba800000, v177
	v_pk_fma_f32 v[64:65], v[66:67], v[66:67], v[64:65]
	v_fmac_f32_e32 v164, 0xba800000, v103
	v_fmac_f32_e32 v162, 0xba800000, v103
	v_mov_b32_e32 v163, v166
	v_pk_mul_f32 v[66:67], v[194:195], v[194:195]
	v_fmamk_f32 v193, v103, 0xba800000, v169
	v_mov_b32_e32 v192, v177
	v_fmamk_f32 v188, v103, 0xba800000, v155
	v_fmac_f32_e32 v154, 0xba800000, v103
	v_pk_fma_f32 v[66:67], v[162:163], v[162:163], v[66:67]
	v_mov_b32_e32 v155, v164
	s_waitcnt lgkmcnt(0)
	v_add_f32_e32 v89, v89, v95
	v_pk_fma_f32 v[64:65], v[192:193], v[192:193], v[64:65]
	v_fmamk_f32 v189, v103, 0xba800000, v165
	v_pk_fma_f32 v[66:67], v[154:155], v[154:155], v[66:67]
	s_nop 1
	v_mov_b32_dpp v95, v89 row_ror:4 row_mask:0xf bank_mask:0xf
	s_nop 1
	v_mov_b32_dpp v107, v105 row_ror:4 row_mask:0xf bank_mask:0xf
	v_pk_fma_f32 v[66:67], v[188:189], v[188:189], v[66:67]
	v_add_f32_e32 v64, v64, v65
	v_add_f32_e32 v64, v67, v64
	v_add_f32_e32 v64, v66, v64
	v_mov_b32_e32 v65, v64
	v_mov_b32_e32 v212, v64
	s_mov_b32 s100, 0
	s_mov_b32 s101, -1
	v_permlane32_swap_b32_e32 v65, v212
	v_cndmask_b32_e64 v65, v212, v65, s[100:101]
	s_waitcnt lgkmcnt(2)
	v_add_f32_e32 v66, v89, v95
	s_waitcnt lgkmcnt(1)
	v_add_f32_e32 v89, v105, v107
	s_nop 1
	v_mov_b32_dpp v95, v89 quad_perm:[2,3,0,1] row_mask:0xf bank_mask:0xf
	s_nop 1
	v_mov_b32_dpp v67, v66 quad_perm:[2,3,0,1] row_mask:0xf bank_mask:0xf
	s_waitcnt lgkmcnt(2)
	v_add_f32_e32 v64, v64, v65
	v_mov_b32_e32 v65, v64
	v_mov_b32_e32 v212, v64
	s_mov_b32 s100, 0xffff0000
	s_mov_b32 s101, 0xffff0000
	v_permlane16_swap_b32_e32 v65, v212
	v_cndmask_b32_e64 v65, v212, v65, s[100:101]
	s_waitcnt lgkmcnt(2)
	v_add_f32_e32 v89, v89, v95
	s_waitcnt lgkmcnt(1)
	v_add_f32_e32 v66, v66, v67
	s_nop 1
	v_mov_b32_dpp v95, v89 quad_perm:[1,0,3,2] row_mask:0xf bank_mask:0xf
	s_nop 1
	v_mov_b32_dpp v67, v66 quad_perm:[1,0,3,2] row_mask:0xf bank_mask:0xf
	s_waitcnt lgkmcnt(2)
	v_add_f32_e32 v64, v64, v65
	s_nop 1
	v_mov_b32_dpp v65, v64 row_ror:8 row_mask:0xf bank_mask:0xf
	s_waitcnt lgkmcnt(2)
	v_add_f32_e32 v89, v89, v95
	s_waitcnt lgkmcnt(1)
	v_add_f32_e32 v66, v66, v67
	v_fmamk_f32 v172, v89, 0xba800000, v83
	v_fmamk_f32 v173, v89, 0xba800000, v79
	v_fmac_f32_e32 v78, 0xba800000, v89
	v_fmamk_f32 v190, v66, 0xba800000, v153
	v_fmamk_f32 v191, v66, 0xba800000, v157
	v_fmac_f32_e32 v156, 0xba800000, v66
	v_fmac_f32_e32 v82, 0xba800000, v89
	v_fmac_f32_e32 v72, 0xba800000, v89
	v_mov_b32_e32 v83, v78
	v_pk_mul_f32 v[144:145], v[172:173], v[172:173]
	s_waitcnt lgkmcnt(0)
	v_add_f32_e32 v95, v64, v65
	v_fmac_f32_e32 v152, 0xba800000, v66
	v_fmac_f32_e32 v140, 0xba800000, v66
	v_mov_b32_e32 v153, v156
	v_pk_mul_f32 v[64:65], v[190:191], v[190:191]
	v_fmamk_f32 v187, v66, 0xba800000, v149
	v_fmac_f32_e32 v148, 0xba800000, v66
	v_fmamk_f32 v186, v66, 0xba800000, v143
	v_fmamk_f32 v158, v89, 0xba800000, v81
	v_fmac_f32_e32 v80, 0xba800000, v89
	v_pk_fma_f32 v[144:145], v[82:83], v[82:83], v[144:145]
	v_mov_b32_e32 v81, v72
	v_fmamk_f32 v161, v89, 0xba800000, v75
	v_fmac_f32_e32 v74, 0xba800000, v89
	v_fmamk_f32 v160, v89, 0xba800000, v77
	v_fmamk_f32 v184, v66, 0xba800000, v151
	v_fmac_f32_e32 v150, 0xba800000, v66
	v_fmamk_f32 v185, v66, 0xba800000, v141
	v_pk_fma_f32 v[64:65], v[152:153], v[152:153], v[64:65]
	v_mov_b32_e32 v151, v140
	v_fmamk_f32 v171, v66, 0xba800000, v147
	v_fmac_f32_e32 v146, 0xba800000, v66
	v_fmamk_f32 v170, v66, 0xba800000, v139
	v_fmac_f32_e32 v138, 0xba800000, v66
	v_fmac_f32_e32 v142, 0xba800000, v66
	v_mov_b32_e32 v143, v148
	v_pk_mul_f32 v[66:67], v[186:187], v[186:187]
	v_fmamk_f32 v159, v89, 0xba800000, v73
	v_pk_fma_f32 v[144:145], v[80:81], v[80:81], v[144:145]
	v_fmac_f32_e32 v70, 0xba800000, v89
	v_fmac_f32_e32 v76, 0xba800000, v89
	v_mov_b32_e32 v77, v74
	v_pk_mul_f32 v[198:199], v[160:161], v[160:161]
	v_pk_fma_f32 v[64:65], v[150:151], v[150:151], v[64:65]
	v_pk_fma_f32 v[66:67], v[142:143], v[142:143], v[66:67]
	v_mov_b32_e32 v139, v146
	v_pk_fma_f32 v[196:197], v[158:159], v[158:159], v[144:145]
	v_fmamk_f32 v144, v89, 0xba800000, v69
	v_fmac_f32_e32 v68, 0xba800000, v89
	v_pk_fma_f32 v[198:199], v[76:77], v[76:77], v[198:199]
	v_mov_b32_e32 v69, v70
	v_pk_fma_f32 v[64:65], v[184:185], v[184:185], v[64:65]
	v_pk_fma_f32 v[66:67], v[138:139], v[138:139], v[66:67]
	v_fmamk_f32 v145, v89, 0xba800000, v71
	v_pk_fma_f32 v[198:199], v[68:69], v[68:69], v[198:199]
	v_pk_fma_f32 v[66:67], v[170:171], v[170:171], v[66:67]
	v_pk_fma_f32 v[198:199], v[144:145], v[144:145], v[198:199]
	v_mov_b32_e32 v200, v196
	v_mov_b32_e32 v201, v64
	v_mov_b32_e32 v64, v197
	v_pk_add_f32 v[64:65], v[200:201], v[64:65]
	v_mov_b32_e32 v196, v199
	v_mov_b32_e32 v197, v67
	v_pk_add_f32 v[64:65], v[196:197], v[64:65]
	v_mov_b32_e32 v199, v66
	v_pk_add_f32 v[64:65], v[198:199], v[64:65]
	v_mov_b32_e32 v67, v65
	v_mov_b32_e32 v212, v65
	s_mov_b32 s100, 0
	s_mov_b32 s101, -1
	v_permlane32_swap_b32_e32 v67, v212
	v_cndmask_b32_e64 v67, v212, v67, s[100:101]
	v_mov_b32_e32 v66, v64
	v_mov_b32_e32 v212, v64
	s_mov_b32 s100, 0
	s_mov_b32 s101, -1
	v_permlane32_swap_b32_e32 v66, v212
	v_cndmask_b32_e64 v66, v212, v66, s[100:101]
	s_nop 1
	v_mov_b32_dpp v103, v95 row_ror:4 row_mask:0xf bank_mask:0xf
	s_waitcnt lgkmcnt(1)
; DI unsigned cvt_pk_bf16(float lo, float hi) { unsigned r; asm volatile("v_cvt_pk_bf16_f32 %0, %1, %2" : "=v"(r) : "v"(lo), "v"(hi)); return r; }
; template <int NR>
; DI void ln_rows(const Args& a, int l, int row0, int lane, const f32x4 (&lgv)[4], const f32x4 (&lbv)[4], const f32x4 (&gate)[4], const f32x4 (&sh)[4], const f32x4 (&sc1)[4]) {
;     ...
;         rstd[k] = rsqrtf(wave_sum(q) * (1.f / 1024.f) + 1e-5f); }
; #pragma unroll
;     for (int k = 0; k < NR; ++k) { const int row = row0 + k;
;         float* zr = row < TL ? a.out + (size_t)row * 1024 : zc + (size_t)(row - TL) * 1024;
; #pragma unroll
;         for (int i = 0; i < 4; ++i) { const int col = 4 * lane + 256 * i;
;             const f32x4 yo = v[k][i] * rstd[k] * lgv[i] + lbv[i];
;             *(f32x4*)(zr + col) = yo;
;             if (l < 3) { const f32x4 hv = yo * sc1[i] + sh[i]; u32x2 w = {cvt_pk_bf16(hv[0], hv[1]), cvt_pk_bf16(hv[2], hv[3])}; *(u32x2*)(h + (size_t)row * 1024 + col) = w; } } }
	v_pk_add_f32 v[64:65], v[64:65], v[66:67]
	v_mov_b32_e32 v67, v65
	v_mov_b32_e32 v212, v65
	s_mov_b32 s100, 0xffff0000
	s_mov_b32 s101, 0xffff0000
	v_permlane16_swap_b32_e32 v67, v212
	v_cndmask_b32_e64 v67, v212, v67, s[100:101]
	v_mov_b32_e32 v66, v64
	v_mov_b32_e32 v212, v64
	s_mov_b32 s100, 0xffff0000
	s_mov_b32 s101, 0xffff0000
	v_permlane16_swap_b32_e32 v66, v212
	v_cndmask_b32_e64 v66, v212, v66, s[100:101]
	s_waitcnt lgkmcnt(2)
	v_add_f32_e32 v69, v95, v103
	s_nop 1
	v_mov_b32_dpp v71, v69 quad_perm:[2,3,0,1] row_mask:0xf bank_mask:0xf
	s_waitcnt lgkmcnt(1)
	v_pk_add_f32 v[64:65], v[64:65], v[66:67]
	s_nop 1
	v_mov_b32_dpp v67, v65 row_ror:8 row_mask:0xf bank_mask:0xf
	s_nop 1
	v_mov_b32_dpp v66, v64 row_ror:8 row_mask:0xf bank_mask:0xf
	s_waitcnt lgkmcnt(2)
	v_add_f32_e32 v69, v69, v71
	s_nop 1
	v_mov_b32_dpp v71, v69 quad_perm:[1,0,3,2] row_mask:0xf bank_mask:0xf
	s_waitcnt lgkmcnt(1)
	v_pk_add_f32 v[64:65], v[64:65], v[66:67]
	s_nop 1
	v_mov_b32_dpp v67, v65 row_ror:4 row_mask:0xf bank_mask:0xf
	s_nop 1
	v_mov_b32_dpp v66, v64 row_ror:4 row_mask:0xf bank_mask:0xf
	s_waitcnt lgkmcnt(2)
	v_add_f32_e32 v69, v69, v71
	v_fmamk_f32 v69, v69, 0x3a800000, v182
	v_mul_f32_e32 v71, 0x4b800000, v69
	v_cmp_gt_f32_e32 vcc, s94, v69
	s_waitcnt lgkmcnt(0)
	v_pk_add_f32 v[64:65], v[64:65], v[66:67]
	s_nop 1
	v_mov_b32_dpp v67, v65 quad_perm:[2,3,0,1] row_mask:0xf bank_mask:0xf
	s_nop 1
	v_mov_b32_dpp v66, v64 quad_perm:[2,3,0,1] row_mask:0xf bank_mask:0xf
	v_cndmask_b32_e32 v69, v69, v71, vcc
	v_rsq_f32_e32 v69, v69
	s_waitcnt lgkmcnt(0)
	v_pk_add_f32 v[196:197], v[64:65], v[66:67]
	v_mul_f32_e32 v71, 0x45800000, v69
	s_nop 1
	v_mov_b32_dpp v199, v197 quad_perm:[1,0,3,2] row_mask:0xf bank_mask:0xf
	s_nop 1
	v_mov_b32_dpp v198, v196 quad_perm:[1,0,3,2] row_mask:0xf bank_mask:0xf
	v_cndmask_b32_e32 v200, v69, v71, vcc
	v_mov_b32_e32 v201, v200
	v_pk_mul_f32 v[64:65], v[178:179], v[200:201] op_sel_hi:[1,0]
	v_pk_mul_f32 v[66:67], v[176:177], v[200:201] op_sel_hi:[1,0]
	v_cndmask_b32_e64 v69, 0, 1, s[16:17]
	v_pk_fma_f32 v[66:67], v[2:3], v[66:67], v[10:11]
	v_pk_fma_f32 v[64:65], v[0:1], v[64:65], v[8:9]
	v_cmp_ne_u32_e64 s[0:1], 1, v69
	s_andn2_b64 vcc, exec, s[16:17]
	v_pk_mul_f32 v[174:175], v[174:175], v[200:201]
	global_store_dwordx4 v[128:129], v[64:67], off offset:-3072 nt
	s_cbranch_vccnz .LBB0_977
	s_nop 0
	v_pk_fma_f32 v[66:67], v[122:123], v[66:67], v[42:43]
	v_pk_fma_f32 v[64:65], v[120:121], v[64:65], v[40:41]
	v_mov_b32_e32 v169, v193
	v_cvt_pk_bf16_f32 v64, v64, v65
	v_cvt_pk_bf16_f32 v65, v66, v67
	v_add_co_u32_e32 v66, vcc, 0xfbc00000, v124
	s_mov_b64 s[8:9], 0
	s_nop 0
	v_addc_co_u32_e32 v67, vcc, -1, v125, vcc
	global_store_dwordx2 v[66:67], v[64:65], off
	v_mov_b32_e32 v64, v200
	v_mov_b32_e32 v65, v200
	v_pk_mul_f32 v[64:65], v[168:169], v[64:65]
	s_nop 0
	v_pk_fma_f32 v[66:67], v[6:7], v[64:65], v[14:15]
	v_pk_fma_f32 v[64:65], v[4:5], v[174:175], v[12:13]
	global_store_dwordx4 v[128:129], v[64:67], off offset:-2048 nt
	s_nop 1
	v_pk_fma_f32 v[66:67], v[118:119], v[66:67], v[46:47]
	v_pk_fma_f32 v[64:65], v[116:117], v[64:65], v[44:45]
	s_nop 0
	v_cvt_pk_bf16_f32 v64, v64, v65
	v_cvt_pk_bf16_f32 v65, v66, v67
	v_add_co_u32_e32 v66, vcc, 0xfbc01000, v124
	s_nop 1
	v_addc_co_u32_e32 v67, vcc, -1, v125, vcc
	global_store_dwordx2 v[66:67], v[64:65], off offset:-3584
.LBB0_977:
	s_andn2_b64 vcc, exec, s[8:9]
	s_cbranch_vccnz .LBB0_979
	v_mov_b32_e32 v64, v200
	v_mov_b32_e32 v65, v200
	v_mov_b32_e32 v169, v193
	v_pk_mul_f32 v[64:65], v[168:169], v[64:65]
	s_nop 0
	v_pk_fma_f32 v[66:67], v[6:7], v[64:65], v[14:15]
	v_pk_fma_f32 v[64:65], v[4:5], v[174:175], v[12:13]
	global_store_dwordx4 v[128:129], v[64:67], off offset:-2048 nt
.LBB0_979:
	v_mov_b32_e32 v167, v195
	v_mov_b32_e32 v168, v200
	v_mov_b32_e32 v169, v200
	v_mov_b32_e32 v165, v189
	v_mov_b32_e32 v163, v194
	v_pk_mul_f32 v[64:65], v[164:165], v[168:169]
	v_pk_mul_f32 v[164:165], v[166:167], v[200:201]
	v_pk_fma_f32 v[66:67], v[18:19], v[64:65], v[26:27]
	v_pk_fma_f32 v[64:65], v[16:17], v[164:165], v[24:25]
	s_mov_b64 s[8:9], -1
	s_and_b64 vcc, exec, s[0:1]
	v_pk_mul_f32 v[162:163], v[162:163], v[200:201]
	global_store_dwordx4 v[128:129], v[64:67], off offset:-1024 nt
	s_cbranch_vccnz .LBB0_981
	s_nop 0
	v_pk_fma_f32 v[64:65], v[112:113], v[64:65], v[36:37]
	v_add_co_u32_e32 v164, vcc, 0xfbc01000, v124
	v_pk_fma_f32 v[66:67], v[114:115], v[66:67], v[38:39]
	v_cvt_pk_bf16_f32 v64, v64, v65
	s_nop 0
	v_addc_co_u32_e32 v165, vcc, -1, v125, vcc
	v_cvt_pk_bf16_f32 v65, v66, v67
	v_mov_b32_e32 v155, v188
	global_store_dwordx2 v[164:165], v[64:65], off offset:-3072
	v_pk_mul_f32 v[64:65], v[154:155], v[168:169]
	s_mov_b64 s[8:9], 0
	v_pk_fma_f32 v[66:67], v[22:23], v[64:65], v[30:31]
	v_pk_fma_f32 v[64:65], v[20:21], v[162:163], v[28:29]
	global_store_dwordx4 v[128:129], v[64:67], off nt
	s_nop 1
	v_pk_fma_f32 v[64:65], v[108:109], v[64:65], v[32:33]
	v_pk_fma_f32 v[66:67], v[110:111], v[66:67], v[34:35]
	v_cvt_pk_bf16_f32 v64, v64, v65
	s_nop 0
	v_cvt_pk_bf16_f32 v65, v66, v67
	global_store_dwordx2 v[164:165], v[64:65], off offset:-2560
.LBB0_981:
	s_andn2_b64 vcc, exec, s[8:9]
	s_cbranch_vccnz .LBB0_983
	v_mov_b32_e32 v201, v200
	v_mov_b32_e32 v155, v188
	v_pk_mul_f32 v[64:65], v[154:155], v[200:201]
	s_nop 0
	v_pk_fma_f32 v[66:67], v[22:23], v[64:65], v[30:31]
	v_pk_fma_f32 v[64:65], v[20:21], v[162:163], v[28:29]
	global_store_dwordx4 v[128:129], v[64:67], off nt
; DI unsigned cvt_pk_bf16(float lo, float hi) { unsigned r; asm volatile("v_cvt_pk_bf16_f32 %0, %1, %2" : "=v"(r) : "v"(lo), "v"(hi)); return r; }
; template <int NR>
; DI void ln_rows(const Args& a, int l, int row0, int lane, const f32x4 (&lgv)[4], const f32x4 (&lbv)[4], const f32x4 (&gate)[4], const f32x4 (&sh)[4], const f32x4 (&sc1)[4]) {
;     ...
;         rstd[k] = rsqrtf(wave_sum(q) * (1.f / 1024.f) + 1e-5f); }
; #pragma unroll
;     for (int k = 0; k < NR; ++k) { const int row = row0 + k;
;         float* zr = row < TL ? a.out + (size_t)row * 1024 : zc + (size_t)(row - TL) * 1024;
; #pragma unroll
;         for (int i = 0; i < 4; ++i) { const int col = 4 * lane + 256 * i;
;             const f32x4 yo = v[k][i] * rstd[k] * lgv[i] + lbv[i];
;             *(f32x4*)(zr + col) = yo;
;             if (l < 3) { const f32x4 hv = yo * sc1[i] + sh[i]; u32x2 w = {cvt_pk_bf16(hv[0], hv[1]), cvt_pk_bf16(hv[2], hv[3])}; *(u32x2*)(h + (size_t)row * 1024 + col) = w; } } }
.LBB0_983:
	s_waitcnt lgkmcnt(0)
	s_nop 0
	v_pk_add_f32 v[64:65], v[196:197], v[198:199]
	s_mov_b32 s8, 0x3a800000
	v_pk_fma_f32 v[154:155], v[64:65], s[8:9], v[182:183] op_sel_hi:[1,0,0]
	v_mov_b32_e32 v153, v190
	v_mul_f32_e32 v64, 0x4b800000, v155
	v_cmp_gt_f32_e32 vcc, s94, v155
	v_mov_b32_e32 v151, v184
	v_mov_b32_e32 v157, v191
	v_cndmask_b32_e32 v64, v155, v64, vcc
	v_rsq_f32_e32 v64, v64
	v_cmp_gt_f32_e64 s[8:9], s94, v154
	v_lshl_add_u64 v[136:137], s[90:91], 0, v[136:137]
	v_lshl_add_u64 v[134:135], v[92:93], 0, v[134:135]
	v_mul_f32_e32 v65, 0x45800000, v64
	v_cndmask_b32_e32 v162, v64, v65, vcc
	v_mov_b32_e32 v163, v162
	v_pk_mul_f32 v[64:65], v[152:153], v[162:163] op_sel_hi:[1,0]
	v_pk_mul_f32 v[66:67], v[150:151], v[162:163] op_sel_hi:[1,0]
	v_pk_fma_f32 v[64:65], v[0:1], v[64:65], v[8:9]
	v_pk_fma_f32 v[66:67], v[2:3], v[66:67], v[10:11]
	s_mov_b64 s[46:47], -1
	s_and_b64 vcc, exec, s[0:1]
	v_pk_mul_f32 v[150:151], v[156:157], v[162:163]
	global_store_dwordx4 v[134:135], v[64:67], off nt
	s_cbranch_vccnz .LBB0_985
	s_nop 0
	v_pk_fma_f32 v[64:65], v[120:121], v[64:65], v[40:41]
	v_mov_b32_e32 v89, v181
	v_pk_fma_f32 v[66:67], v[122:123], v[66:67], v[42:43]
	v_cvt_pk_bf16_f32 v64, v64, v65
	v_lshl_add_u64 v[152:153], v[136:137], 0, v[88:89]
	v_cvt_pk_bf16_f32 v65, v66, v67
	global_store_dwordx2 v[152:153], v[64:65], off
	v_mov_b32_e32 v64, v162
	v_mov_b32_e32 v65, v162
	v_mov_b32_e32 v141, v185
	v_pk_mul_f32 v[64:65], v[140:141], v[64:65]
	s_mov_b64 s[46:47], 0
	v_pk_fma_f32 v[66:67], v[6:7], v[64:65], v[14:15]
	v_pk_fma_f32 v[64:65], v[4:5], v[150:151], v[12:13]
	global_store_dwordx4 v[134:135], v[64:67], off offset:1024 nt
	s_nop 1
	v_pk_fma_f32 v[64:65], v[116:117], v[64:65], v[44:45]
	v_pk_fma_f32 v[66:67], v[118:119], v[66:67], v[46:47]
	v_cvt_pk_bf16_f32 v64, v64, v65
	s_nop 0
	v_cvt_pk_bf16_f32 v65, v66, v67
	global_store_dwordx2 v[152:153], v[64:65], off offset:512
.LBB0_985:
	s_andn2_b64 vcc, exec, s[46:47]
	s_cbranch_vccnz .LBB0_987
	v_mov_b32_e32 v64, v162
	v_mov_b32_e32 v65, v162
	v_mov_b32_e32 v141, v185
	v_pk_mul_f32 v[64:65], v[140:141], v[64:65]
	s_nop 0
	v_pk_fma_f32 v[66:67], v[6:7], v[64:65], v[14:15]
	v_pk_fma_f32 v[64:65], v[4:5], v[150:151], v[12:13]
	global_store_dwordx4 v[134:135], v[64:67], off offset:1024 nt
.LBB0_987:
	v_mov_b32_e32 v149, v187
	v_mov_b32_e32 v150, v162
	v_mov_b32_e32 v151, v162
	v_mov_b32_e32 v147, v171
	v_mov_b32_e32 v143, v186
	v_pk_mul_f32 v[64:65], v[146:147], v[150:151]
	v_pk_mul_f32 v[140:141], v[148:149], v[162:163]
	v_pk_fma_f32 v[66:67], v[18:19], v[64:65], v[26:27]
	v_pk_fma_f32 v[64:65], v[16:17], v[140:141], v[24:25]
	s_mov_b64 s[46:47], -1
	s_and_b64 vcc, exec, s[0:1]
	v_pk_mul_f32 v[140:141], v[142:143], v[162:163]
	global_store_dwordx4 v[134:135], v[64:67], off offset:2048 nt
	s_cbranch_vccnz .LBB0_989
	s_nop 0
	v_pk_fma_f32 v[64:65], v[112:113], v[64:65], v[36:37]
	v_mov_b32_e32 v89, v181
	v_pk_fma_f32 v[66:67], v[114:115], v[66:67], v[38:39]
	v_cvt_pk_bf16_f32 v64, v64, v65
	v_lshl_add_u64 v[136:137], v[136:137], 0, v[88:89]
	v_cvt_pk_bf16_f32 v65, v66, v67
	v_mov_b32_e32 v139, v170
	global_store_dwordx2 v[136:137], v[64:65], off offset:1024
	v_pk_mul_f32 v[64:65], v[138:139], v[150:151]
	s_mov_b64 s[46:47], 0
	v_pk_fma_f32 v[66:67], v[22:23], v[64:65], v[30:31]
	v_pk_fma_f32 v[64:65], v[20:21], v[140:141], v[28:29]
	global_store_dwordx4 v[134:135], v[64:67], off offset:3072 nt
	s_nop 1
	v_pk_fma_f32 v[64:65], v[108:109], v[64:65], v[32:33]
	v_pk_fma_f32 v[66:67], v[110:111], v[66:67], v[34:35]
	v_cvt_pk_bf16_f32 v64, v64, v65
	s_nop 0
	v_cvt_pk_bf16_f32 v65, v66, v67
	global_store_dwordx2 v[136:137], v[64:65], off offset:1536
.LBB0_989:
	s_andn2_b64 vcc, exec, s[46:47]
	s_cbranch_vccnz .LBB0_991
	v_mov_b32_e32 v163, v162
	v_mov_b32_e32 v139, v170
	v_pk_mul_f32 v[64:65], v[138:139], v[162:163]
	s_nop 0
	v_pk_fma_f32 v[66:67], v[22:23], v[64:65], v[30:31]
	v_pk_fma_f32 v[64:65], v[20:21], v[140:141], v[28:29]
	global_store_dwordx4 v[134:135], v[64:67], off offset:3072 nt
.LBB0_991:
	s_nop 1
	v_mul_f32_e32 v64, 0x4b800000, v154
	v_cndmask_b32_e64 v64, v154, v64, s[8:9]
	v_rsq_f32_e32 v66, v64
	v_lshl_add_u64 v[64:65], s[26:27], 0, v[132:133]
	v_mov_b32_e32 v83, v172
	v_mov_b32_e32 v81, v158
	v_mul_f32_e32 v67, 0x45800000, v66
	v_cndmask_b32_e64 v132, v66, v67, s[8:9]
	v_mov_b32_e32 v66, s85
	v_cndmask_b32_e64 v135, v66, v65, s[6:7]
	v_mov_b32_e32 v65, s84
	v_mov_b32_e32 v133, v132
	v_mov_b32_e32 v79, v173
	v_cndmask_b32_e64 v134, v65, v64, s[6:7]
	v_pk_mul_f32 v[64:65], v[82:83], v[132:133] op_sel_hi:[1,0]
	v_pk_mul_f32 v[66:67], v[80:81], v[132:133] op_sel_hi:[1,0]
	v_lshl_add_u64 v[130:131], s[90:91], 0, v[130:131]
	v_pk_fma_f32 v[66:67], v[2:3], v[66:67], v[10:11]
	v_pk_fma_f32 v[64:65], v[0:1], v[64:65], v[8:9]
	v_lshl_add_u64 v[80:81], v[134:135], 0, v[180:181]
	s_mov_b64 s[6:7], -1
	s_and_b64 vcc, exec, s[0:1]
	v_pk_mul_f32 v[78:79], v[78:79], v[132:133]
	global_store_dwordx4 v[80:81], v[64:67], off nt
	s_cbranch_vccnz .LBB0_993
	s_nop 0
	v_pk_fma_f32 v[64:65], v[120:121], v[64:65], v[40:41]
	v_mov_b32_e32 v89, v181
	v_pk_fma_f32 v[66:67], v[122:123], v[66:67], v[42:43]
	v_cvt_pk_bf16_f32 v64, v64, v65
	v_lshl_add_u64 v[82:83], v[130:131], 0, v[88:89]
	v_cvt_pk_bf16_f32 v65, v66, v67
	global_store_dwordx2 v[82:83], v[64:65], off
	v_mov_b32_e32 v64, v132
	v_mov_b32_e32 v65, v132
	v_mov_b32_e32 v73, v159
	v_pk_mul_f32 v[64:65], v[72:73], v[64:65]
	s_mov_b64 s[6:7], 0
	v_pk_fma_f32 v[66:67], v[6:7], v[64:65], v[14:15]
	v_pk_fma_f32 v[64:65], v[4:5], v[78:79], v[12:13]
	global_store_dwordx4 v[80:81], v[64:67], off offset:1024 nt
	s_nop 1
	v_pk_fma_f32 v[64:65], v[116:117], v[64:65], v[44:45]
	v_pk_fma_f32 v[66:67], v[118:119], v[66:67], v[46:47]
	v_cvt_pk_bf16_f32 v64, v64, v65
	s_nop 0
	v_cvt_pk_bf16_f32 v65, v66, v67
	global_store_dwordx2 v[82:83], v[64:65], off offset:512
; DI unsigned cvt_pk_bf16(float lo, float hi) { unsigned r; asm volatile("v_cvt_pk_bf16_f32 %0, %1, %2" : "=v"(r) : "v"(lo), "v"(hi)); return r; }
; DI float bflo(unsigned w) { return __uint_as_float(w << 16); }
; DI float bfhi(unsigned w) { return __uint_as_float(w & 0xffff0000u); }
; template <int NR>
; DI void ln_rows(const Args& a, int l, int row0, int lane, const f32x4 (&lgv)[4], const f32x4 (&lbv)[4], const f32x4 (&gate)[4], const f32x4 (&sh)[4], const f32x4 (&sc1)[4]) {
;     ...
;     for (int k = 0; k < NR; ++k) { const int row = row0 + k; s[k] = 0.f;
;         const float* xr = row < TL ? xlat + (size_t)row * 1024 : xctx + (size_t)(row - TL) * 1024;
; #pragma unroll
;         for (int i = 0; i < 4; ++i) { const int col = 4 * lane + 256 * i;
;             const f32x4 xv = *(const f32x4*)(xr + col); const u32x2 yw = *(const u32x2*)(y + (size_t)row * 1024 + col);
;             f32x4 yv; yv[0] = bflo(yw[0]); yv[1] = bfhi(yw[0]); yv[2] = bflo(yw[1]); yv[3] = bfhi(yw[1]);
;             v[k][i] = xv * ALPHA + gate[i] * yv; s[k] += v[k][i][0] + v[k][i][1] + v[k][i][2] + v[k][i][3]; } }
;     float mean[NR], rstd[NR];
; #pragma unroll
;     for (int k = 0; k < NR; ++k) mean[k] = wave_sum(s[k]) * (1.f / 1024.f);
;     ...
;     for (int k = 0; k < NR; ++k) { const int row = row0 + k;
;         float* zr = row < TL ? a.out + (size_t)row * 1024 : zc + (size_t)(row - TL) * 1024;
; #pragma unroll
;         for (int i = 0; i < 4; ++i) { const int col = 4 * lane + 256 * i;
;             const f32x4 yo = v[k][i] * rstd[k] * lgv[i] + lbv[i];
;             *(f32x4*)(zr + col) = yo;
;             if (l < 3) { const f32x4 hv = yo * sc1[i] + sh[i]; u32x2 w = {cvt_pk_bf16(hv[0], hv[1]), cvt_pk_bf16(hv[2], hv[3])}; *(u32x2*)(h + (size_t)row * 1024 + col) = w; } } }
.LBB0_993:
	s_andn2_b64 vcc, exec, s[6:7]
	s_cbranch_vccnz .LBB0_995
	v_mov_b32_e32 v64, v132
	v_mov_b32_e32 v65, v132
	v_mov_b32_e32 v73, v159
	v_pk_mul_f32 v[64:65], v[72:73], v[64:65]
	s_nop 0
	v_pk_fma_f32 v[66:67], v[6:7], v[64:65], v[14:15]
	v_pk_fma_f32 v[64:65], v[4:5], v[78:79], v[12:13]
	global_store_dwordx4 v[80:81], v[64:67], off offset:1024 nt
.LBB0_995:
	v_mov_b32_e32 v75, v161
	v_mov_b32_e32 v72, v132
	v_mov_b32_e32 v73, v132
	v_mov_b32_e32 v71, v145
	v_mov_b32_e32 v77, v160
	v_pk_mul_f32 v[64:65], v[70:71], v[72:73]
	v_pk_mul_f32 v[70:71], v[74:75], v[132:133]
	v_pk_fma_f32 v[66:67], v[18:19], v[64:65], v[26:27]
	v_pk_fma_f32 v[64:65], v[16:17], v[70:71], v[24:25]
	s_mov_b64 s[6:7], -1
	s_and_b64 vcc, exec, s[0:1]
	v_pk_mul_f32 v[70:71], v[76:77], v[132:133]
	global_store_dwordx4 v[80:81], v[64:67], off offset:2048 nt
	s_cbranch_vccnz .LBB0_997
	s_nop 0
	v_pk_fma_f32 v[64:65], v[112:113], v[64:65], v[36:37]
	v_mov_b32_e32 v89, v181
	v_pk_fma_f32 v[66:67], v[114:115], v[66:67], v[38:39]
	v_cvt_pk_bf16_f32 v64, v64, v65
	v_lshl_add_u64 v[74:75], v[130:131], 0, v[88:89]
	v_cvt_pk_bf16_f32 v65, v66, v67
	v_mov_b32_e32 v69, v144
	global_store_dwordx2 v[74:75], v[64:65], off offset:1024
	v_pk_mul_f32 v[64:65], v[68:69], v[72:73]
	s_mov_b64 s[6:7], 0
	v_pk_fma_f32 v[66:67], v[22:23], v[64:65], v[30:31]
	v_pk_fma_f32 v[64:65], v[20:21], v[70:71], v[28:29]
	global_store_dwordx4 v[80:81], v[64:67], off offset:3072 nt
	s_nop 1
	v_pk_fma_f32 v[64:65], v[108:109], v[64:65], v[32:33]
	v_pk_fma_f32 v[66:67], v[110:111], v[66:67], v[34:35]
	v_cvt_pk_bf16_f32 v64, v64, v65
	s_nop 0
	v_cvt_pk_bf16_f32 v65, v66, v67
	global_store_dwordx2 v[74:75], v[64:65], off offset:1536
.LBB0_997:
	s_andn2_b64 vcc, exec, s[6:7]
	s_cbranch_vccnz .LBB0_974
	v_mov_b32_e32 v133, v132
	v_mov_b32_e32 v69, v144
	v_pk_mul_f32 v[64:65], v[68:69], v[132:133]
	s_nop 0
	v_pk_fma_f32 v[66:67], v[22:23], v[64:65], v[30:31]
	v_pk_fma_f32 v[64:65], v[20:21], v[70:71], v[28:29]
	global_store_dwordx4 v[80:81], v[64:67], off offset:3072 nt
	s_branch .LBB0_974
.LBB0_999:
	v_lshlrev_b32_e32 v64, 4, v211
	v_or_b32_e32 v68, 15, v64
	s_mov_b32 s6, 0x8000
	v_add_u32_e32 v64, 0xffff800f, v64
	v_mov_b32_e32 v65, v181
	v_ashrrev_i32_e32 v69, 31, v68
	v_cmp_gt_i32_e32 vcc, s6, v68
	v_lshlrev_b64 v[64:65], 12, v[64:65]
	v_lshlrev_b64 v[66:67], 12, v[68:69]
	v_lshlrev_b64 v[68:69], 11, v[68:69]
	v_lshl_add_u64 v[70:71], s[20:21], 0, v[64:65]
	v_lshl_add_u64 v[72:73], s[18:19], 0, v[66:67]
	v_lshl_add_u64 v[76:77], v[90:91], 0, v[68:69]
	v_cndmask_b32_e32 v71, v71, v73, vcc
	v_cndmask_b32_e32 v70, v70, v72, vcc
	global_load_dwordx2 v[78:79], v[76:77], off
	v_lshl_add_u64 v[74:75], v[70:71], 0, v[180:181]
	global_load_dwordx4 v[70:73], v[74:75], off nt
	s_waitcnt vmcnt(1)
	v_lshlrev_b32_e32 v80, 16, v78
	v_and_b32_e32 v81, 0xffff0000, v78
	v_lshlrev_b32_e32 v78, 16, v79
	v_and_b32_e32 v79, 0xffff0000, v79
	v_pk_mul_f32 v[80:81], v[60:61], v[80:81]
	v_pk_mul_f32 v[60:61], v[62:63], v[78:79]
	s_waitcnt vmcnt(0)
	v_pk_fma_f32 v[62:63], v[70:71], s[44:45], v[80:81] op_sel_hi:[1,0,1]
	v_pk_fma_f32 v[60:61], v[72:73], s[44:45], v[60:61] op_sel_hi:[1,0,1]
	global_load_dwordx4 v[70:73], v[74:75], off offset:1024 nt
	global_load_dwordx2 v[78:79], v[76:77], off offset:512
	s_waitcnt vmcnt(0)
	v_lshlrev_b32_e32 v80, 16, v78
	v_and_b32_e32 v81, 0xffff0000, v78
	v_lshlrev_b32_e32 v78, 16, v79
	v_and_b32_e32 v79, 0xffff0000, v79
	v_pk_mul_f32 v[80:81], v[56:57], v[80:81]
	v_pk_mul_f32 v[56:57], v[58:59], v[78:79]
	v_pk_fma_f32 v[58:59], v[70:71], s[44:45], v[80:81] op_sel_hi:[1,0,1]
	v_pk_fma_f32 v[56:57], v[72:73], s[44:45], v[56:57] op_sel_hi:[1,0,1]
	v_mov_b32_e32 v70, v62
	v_mov_b32_e32 v71, v58
	v_mov_b32_e32 v72, v63
	v_mov_b32_e32 v73, v59
	v_pk_add_f32 v[70:71], v[70:71], v[72:73]
	v_mov_b32_e32 v72, v60
	v_mov_b32_e32 v73, v56
	v_pk_add_f32 v[70:71], v[72:73], v[70:71]
	v_mov_b32_e32 v72, v61
	v_mov_b32_e32 v73, v57
	v_pk_add_f32 v[70:71], v[72:73], v[70:71]
	s_nop 0
	v_add_f32_e32 v70, 0, v70
	v_add_f32_e32 v82, v70, v71
	global_load_dwordx4 v[70:73], v[74:75], off offset:2048 nt
	global_load_dwordx2 v[78:79], v[76:77], off offset:1024
	s_waitcnt vmcnt(0)
	v_lshlrev_b32_e32 v80, 16, v78
	v_and_b32_e32 v81, 0xffff0000, v78
	v_lshlrev_b32_e32 v78, 16, v79
	v_and_b32_e32 v79, 0xffff0000, v79
	v_pk_mul_f32 v[80:81], v[52:53], v[80:81]
	v_pk_mul_f32 v[52:53], v[54:55], v[78:79]
	v_pk_fma_f32 v[54:55], v[70:71], s[44:45], v[80:81] op_sel_hi:[1,0,1]
	v_pk_fma_f32 v[52:53], v[72:73], s[44:45], v[52:53] op_sel_hi:[1,0,1]
	global_load_dwordx4 v[72:75], v[74:75], off offset:3072 nt
	s_nop 0
	global_load_dwordx2 v[70:71], v[76:77], off offset:1536
	s_waitcnt vmcnt(0)
	v_lshlrev_b32_e32 v76, 16, v70
	v_and_b32_e32 v77, 0xffff0000, v70
	v_lshlrev_b32_e32 v70, 16, v71
	v_and_b32_e32 v71, 0xffff0000, v71
	v_pk_mul_f32 v[48:49], v[48:49], v[76:77]
	v_pk_mul_f32 v[50:51], v[50:51], v[70:71]
	v_pk_fma_f32 v[72:73], v[72:73], s[44:45], v[48:49] op_sel_hi:[1,0,1]
	v_pk_fma_f32 v[70:71], v[74:75], s[44:45], v[50:51] op_sel_hi:[1,0,1]
	v_mov_b32_e32 v48, v54
	v_mov_b32_e32 v49, v72
	v_mov_b32_e32 v50, v55
	v_mov_b32_e32 v51, v73
	v_pk_add_f32 v[48:49], v[48:49], v[50:51]
	v_mov_b32_e32 v50, v52
	v_mov_b32_e32 v51, v70
	v_pk_add_f32 v[48:49], v[50:51], v[48:49]
	v_mov_b32_e32 v50, v53
	v_mov_b32_e32 v51, v71
	v_pk_add_f32 v[48:49], v[50:51], v[48:49]
	s_nop 0
	v_add_f32_e32 v48, v82, v48
	v_add_f32_e32 v48, v48, v49
	v_mov_b32_e32 v49, v48
	v_mov_b32_e32 v212, v48
	s_mov_b32 s100, 0
	s_mov_b32 s101, -1
	v_permlane32_swap_b32_e32 v49, v212
	v_cndmask_b32_e64 v49, v212, v49, s[100:101]
	s_waitcnt lgkmcnt(0)
; DI unsigned cvt_pk_bf16(float lo, float hi) { unsigned r; asm volatile("v_cvt_pk_bf16_f32 %0, %1, %2" : "=v"(r) : "v"(lo), "v"(hi)); return r; }
; template <int NR>
; DI void ln_rows(const Args& a, int l, int row0, int lane, const f32x4 (&lgv)[4], const f32x4 (&lbv)[4], const f32x4 (&gate)[4], const f32x4 (&sh)[4], const f32x4 (&sc1)[4]) {
;     ...
;     for (int k = 0; k < NR; ++k) mean[k] = wave_sum(s[k]) * (1.f / 1024.f);
; #pragma unroll
;     for (int k = 0; k < NR; ++k) { float q = 0.f;
; #pragma unroll
;         for (int i = 0; i < 4; ++i) { v[k][i] = v[k][i] - mean[k]; q += v[k][i][0] * v[k][i][0] + v[k][i][1] * v[k][i][1] + v[k][i][2] * v[k][i][2] + v[k][i][3] * v[k][i][3]; }
;         rstd[k] = rsqrtf(wave_sum(q) * (1.f / 1024.f) + 1e-5f); }
; #pragma unroll
;     for (int k = 0; k < NR; ++k) { const int row = row0 + k;
;         float* zr = row < TL ? a.out + (size_t)row * 1024 : zc + (size_t)(row - TL) * 1024;
; #pragma unroll
;         for (int i = 0; i < 4; ++i) { const int col = 4 * lane + 256 * i;
;             const f32x4 yo = v[k][i] * rstd[k] * lgv[i] + lbv[i];
;             *(f32x4*)(zr + col) = yo;
;             if (l < 3) { const f32x4 hv = yo * sc1[i] + sh[i]; u32x2 w = {cvt_pk_bf16(hv[0], hv[1]), cvt_pk_bf16(hv[2], hv[3])}; *(u32x2*)(h + (size_t)row * 1024 + col) = w; } } }
	v_add_f32_e32 v48, v48, v49
	v_mov_b32_e32 v49, v48
	v_mov_b32_e32 v212, v48
	s_mov_b32 s100, 0xffff0000
	s_mov_b32 s101, 0xffff0000
	v_permlane16_swap_b32_e32 v49, v212
	v_cndmask_b32_e64 v49, v212, v49, s[100:101]
	s_waitcnt lgkmcnt(0)
	v_add_f32_e32 v48, v48, v49
	s_nop 1
	v_mov_b32_dpp v49, v48 row_ror:8 row_mask:0xf bank_mask:0xf
	s_waitcnt lgkmcnt(0)
	v_add_f32_e32 v48, v48, v49
	s_nop 1
	v_mov_b32_dpp v49, v48 row_ror:4 row_mask:0xf bank_mask:0xf
	s_waitcnt lgkmcnt(0)
	v_add_f32_e32 v48, v48, v49
	s_nop 1
	v_mov_b32_dpp v49, v48 quad_perm:[2,3,0,1] row_mask:0xf bank_mask:0xf
	s_waitcnt lgkmcnt(0)
	v_add_f32_e32 v48, v48, v49
	s_nop 1
	v_mov_b32_dpp v49, v48 quad_perm:[1,0,3,2] row_mask:0xf bank_mask:0xf
	s_waitcnt lgkmcnt(0)
	v_add_f32_e32 v75, v48, v49
	v_fmamk_f32 v63, v75, 0xba800000, v63
	v_fmamk_f32 v59, v75, 0xba800000, v59
	v_fmac_f32_e32 v62, 0xba800000, v75
	v_fmac_f32_e32 v58, 0xba800000, v75
	v_mov_b32_e32 v50, v63
	v_mov_b32_e32 v51, v59
	v_fmac_f32_e32 v60, 0xba800000, v75
	v_fmac_f32_e32 v56, 0xba800000, v75
	v_mov_b32_e32 v48, v62
	v_mov_b32_e32 v49, v58
	v_pk_mul_f32 v[50:51], v[50:51], v[50:51]
	v_fmamk_f32 v55, v75, 0xba800000, v55
	v_fmamk_f32 v73, v75, 0xba800000, v73
	v_pk_fma_f32 v[48:49], v[48:49], v[48:49], v[50:51]
	v_mov_b32_e32 v50, v60
	v_mov_b32_e32 v51, v56
	v_fmac_f32_e32 v54, 0xba800000, v75
	v_fmac_f32_e32 v72, 0xba800000, v75
	v_mov_b32_e32 v78, v73
	v_mov_b32_e32 v79, v55
	v_fmamk_f32 v61, v75, 0xba800000, v61
	v_pk_fma_f32 v[48:49], v[50:51], v[50:51], v[48:49]
	v_fmac_f32_e32 v52, 0xba800000, v75
	v_mov_b32_e32 v50, v72
	v_mov_b32_e32 v51, v54
	v_pk_mul_f32 v[78:79], v[78:79], v[78:79]
	v_fmamk_f32 v77, v75, 0xba800000, v57
	v_mov_b32_e32 v76, v61
	v_fmamk_f32 v53, v75, 0xba800000, v53
	v_fmamk_f32 v74, v75, 0xba800000, v71
	v_fmac_f32_e32 v70, 0xba800000, v75
	v_pk_fma_f32 v[50:51], v[50:51], v[50:51], v[78:79]
	v_mov_b32_e32 v71, v52
	v_pk_fma_f32 v[48:49], v[76:77], v[76:77], v[48:49]
	v_pk_fma_f32 v[50:51], v[70:71], v[70:71], v[50:51]
	v_mov_b32_e32 v75, v53
	v_pk_fma_f32 v[50:51], v[74:75], v[74:75], v[50:51]
	v_add_f32_e32 v48, v48, v49
	v_add_f32_e32 v48, v51, v48
	v_add_f32_e32 v48, v50, v48
	v_mov_b32_e32 v49, v48
	v_mov_b32_e32 v212, v48
	s_mov_b32 s100, 0
	s_mov_b32 s101, -1
	v_permlane32_swap_b32_e32 v49, v212
	v_cndmask_b32_e64 v49, v212, v49, s[100:101]
	v_lshl_add_u64 v[50:51], s[26:27], 0, v[66:67]
	s_waitcnt lgkmcnt(0)
	v_add_f32_e32 v48, v48, v49
	v_mov_b32_e32 v49, v48
	v_mov_b32_e32 v212, v48
	s_mov_b32 s100, 0xffff0000
	s_mov_b32 s101, 0xffff0000
	v_permlane16_swap_b32_e32 v49, v212
	v_cndmask_b32_e64 v49, v212, v49, s[100:101]
	s_waitcnt lgkmcnt(0)
	v_add_f32_e32 v48, v48, v49
	s_nop 1
	v_mov_b32_dpp v49, v48 row_ror:8 row_mask:0xf bank_mask:0xf
	s_waitcnt lgkmcnt(0)
	v_add_f32_e32 v48, v48, v49
	s_nop 1
	v_mov_b32_dpp v49, v48 row_ror:4 row_mask:0xf bank_mask:0xf
	s_waitcnt lgkmcnt(0)
	v_add_f32_e32 v48, v48, v49
	s_nop 1
	v_mov_b32_dpp v49, v48 quad_perm:[2,3,0,1] row_mask:0xf bank_mask:0xf
	s_waitcnt lgkmcnt(0)
	v_add_f32_e32 v48, v48, v49
	s_nop 1
	v_mov_b32_dpp v49, v48 quad_perm:[1,0,3,2] row_mask:0xf bank_mask:0xf
	s_waitcnt lgkmcnt(0)
	v_add_f32_e32 v48, v48, v49
	v_fmamk_f32 v48, v48, 0x3a800000, v182
	v_cmp_gt_f32_e64 s[6:7], s94, v48
	v_mul_f32_e32 v49, 0x4b800000, v48
	s_nop 0
	v_cndmask_b32_e64 v48, v48, v49, s[6:7]
	v_rsq_f32_e32 v48, v48
	s_nop 0
	v_mul_f32_e32 v49, 0x45800000, v48
	v_cndmask_b32_e64 v78, v48, v49, s[6:7]
	v_lshl_add_u64 v[48:49], s[84:85], 0, v[64:65]
	v_mov_b32_e32 v80, v78
	v_mov_b32_e32 v81, v78
	v_cndmask_b32_e32 v67, v49, v51, vcc
	v_cndmask_b32_e32 v66, v48, v50, vcc
	v_pk_mul_f32 v[48:49], v[62:63], v[78:79] op_sel_hi:[1,0]
	v_pk_mul_f32 v[50:51], v[60:61], v[78:79] op_sel_hi:[1,0]
	v_lshl_add_u64 v[64:65], s[90:91], 0, v[68:69]
	v_pk_fma_f32 v[50:51], v[2:3], v[50:51], v[10:11]
	v_pk_fma_f32 v[48:49], v[0:1], v[48:49], v[8:9]
	v_lshl_add_u64 v[60:61], v[66:67], 0, v[180:181]
	s_mov_b64 s[6:7], -1
	s_and_b64 vcc, exec, s[0:1]
	v_pk_mul_f32 v[58:59], v[58:59], v[80:81]
	global_store_dwordx4 v[60:61], v[48:51], off nt
	s_cbranch_vccnz .LBB0_1001
	v_pk_fma_f32 v[40:41], v[120:121], v[48:49], v[40:41]
	v_mov_b32_e32 v89, v181
	v_pk_fma_f32 v[42:43], v[122:123], v[50:51], v[42:43]
	v_cvt_pk_bf16_f32 v40, v40, v41
	v_lshl_add_u64 v[48:49], v[64:65], 0, v[88:89]
	v_cvt_pk_bf16_f32 v41, v42, v43
	v_mov_b32_e32 v79, v78
	v_mov_b32_e32 v57, v77
	global_store_dwordx2 v[48:49], v[40:41], off
	v_pk_mul_f32 v[40:41], v[56:57], v[78:79]
	s_mov_b64 s[6:7], 0
	v_pk_fma_f32 v[42:43], v[6:7], v[40:41], v[14:15]
	v_pk_fma_f32 v[40:41], v[4:5], v[58:59], v[12:13]
	global_store_dwordx4 v[60:61], v[40:43], off offset:1024 nt
	s_nop 1
	v_pk_fma_f32 v[40:41], v[116:117], v[40:41], v[44:45]
	v_pk_fma_f32 v[42:43], v[118:119], v[42:43], v[46:47]
	v_cvt_pk_bf16_f32 v40, v40, v41
	s_nop 0
	v_cvt_pk_bf16_f32 v41, v42, v43
	global_store_dwordx2 v[48:49], v[40:41], off offset:512
.LBB0_1001:
	s_andn2_b64 vcc, exec, s[6:7]
	s_cbranch_vccnz .LBB0_1003
	v_mov_b32_e32 v79, v78
	v_mov_b32_e32 v57, v77
	v_pk_mul_f32 v[40:41], v[56:57], v[78:79]
	s_nop 0
	v_pk_fma_f32 v[42:43], v[6:7], v[40:41], v[14:15]
	v_pk_fma_f32 v[40:41], v[4:5], v[58:59], v[12:13]
	global_store_dwordx4 v[60:61], v[40:43], off offset:1024 nt
.LBB0_1003:
	v_mov_b32_e32 v79, v78
	s_nop 0
	v_pk_mul_f32 v[40:41], v[52:53], v[78:79]
	v_pk_mul_f32 v[44:45], v[54:55], v[80:81]
	v_pk_fma_f32 v[42:43], v[18:19], v[40:41], v[26:27]
	v_pk_fma_f32 v[40:41], v[16:17], v[44:45], v[24:25]
	s_mov_b64 s[6:7], -1
	s_and_b64 vcc, exec, s[0:1]
	v_pk_mul_f32 v[44:45], v[72:73], v[80:81]
	global_store_dwordx4 v[60:61], v[40:43], off offset:2048 nt
	s_cbranch_vccnz .LBB0_1005
	v_pk_fma_f32 v[36:37], v[112:113], v[40:41], v[36:37]
	v_mov_b32_e32 v89, v181
	v_pk_fma_f32 v[38:39], v[114:115], v[42:43], v[38:39]
	v_cvt_pk_bf16_f32 v36, v36, v37
	v_lshl_add_u64 v[40:41], v[64:65], 0, v[88:89]
	v_cvt_pk_bf16_f32 v37, v38, v39
	v_mov_b32_e32 v71, v74
	global_store_dwordx2 v[40:41], v[36:37], off offset:1024
	v_pk_mul_f32 v[36:37], v[70:71], v[78:79]
	s_mov_b64 s[6:7], 0
	v_pk_fma_f32 v[38:39], v[22:23], v[36:37], v[30:31]
	v_pk_fma_f32 v[36:37], v[20:21], v[44:45], v[28:29]
	global_store_dwordx4 v[60:61], v[36:39], off offset:3072 nt
	v_pk_fma_f32 v[32:33], v[108:109], v[36:37], v[32:33]
	v_pk_fma_f32 v[34:35], v[110:111], v[38:39], v[34:35]
	v_cvt_pk_bf16_f32 v32, v32, v33
	s_nop 0
	v_cvt_pk_bf16_f32 v33, v34, v35
	global_store_dwordx2 v[40:41], v[32:33], off offset:1536
.LBB0_1005:
	s_andn2_b64 vcc, exec, s[6:7]
	s_movk_i32 s0, 0x7ff
	s_cbranch_vccnz .LBB0_972
	v_mov_b32_e32 v79, v78
	v_mov_b32_e32 v71, v74
	v_pk_mul_f32 v[32:33], v[70:71], v[78:79]
	s_nop 0
	v_pk_fma_f32 v[34:35], v[22:23], v[32:33], v[30:31]
	v_pk_fma_f32 v[32:33], v[20:21], v[44:45], v[28:29]
	global_store_dwordx4 v[60:61], v[32:35], off offset:3072 nt
	s_branch .LBB0_972

; DI float bflo(unsigned w) { return __uint_as_float(w << 16); }
; DI float bfhi(unsigned w) { return __uint_as_float(w & 0xffff0000u); }
; template <int NR>
; DI void ln_rows(const Args& a, int l, int row0, int lane, const f32x4 (&lgv)[4], const f32x4 (&lbv)[4], const f32x4 (&gate)[4], const f32x4 (&sh)[4], const f32x4 (&sc1)[4]) {
;     ...
;     for (int k = 0; k < NR; ++k) { const int row = row0 + k; s[k] = 0.f;
;         const float* xr = row < TL ? xlat + (size_t)row * 1024 : xctx + (size_t)(row - TL) * 1024;
; #pragma unroll
;         for (int i = 0; i < 4; ++i) { const int col = 4 * lane + 256 * i;
;             const f32x4 xv = *(const f32x4*)(xr + col); const u32x2 yw = *(const u32x2*)(y + (size_t)row * 1024 + col);
;             f32x4 yv; yv[0] = bflo(yw[0]); yv[1] = bfhi(yw[0]); yv[2] = bflo(yw[1]); yv[3] = bfhi(yw[1]);
;             v[k][i] = xv * ALPHA + gate[i] * yv; s[k] += v[k][i][0] + v[k][i][1] + v[k][i][2] + v[k][i][3]; } }
;     float mean[NR], rstd[NR];
; #pragma unroll
;     for (int k = 0; k < NR; ++k) mean[k] = wave_sum(s[k]) * (1.f / 1024.f);
.LBB0_1010:
	v_add_u32_e32 v88, 0x8000, v84
	v_mov_b32_e32 v85, v181
	v_ashrrev_i32_e32 v89, 31, v88
	v_lshlrev_b64 v[90:91], 12, v[84:85]
	v_lshlrev_b64 v[92:93], 12, v[88:89]
	v_lshlrev_b64 v[100:101], 11, v[88:89]
	v_lshl_add_u64 v[86:87], s[6:7], 0, v[90:91]
	v_lshl_add_u64 v[88:89], s[84:85], 0, v[90:91]
	v_lshl_add_u64 v[90:91], s[4:5], 0, v[92:93]
	v_cmp_gt_i32_e32 vcc, 0, v84
	v_lshl_add_u64 v[102:103], v[80:81], 0, v[100:101]
	v_lshl_add_u64 v[104:105], s[26:27], 0, v[92:93]
	global_load_dwordx2 v[112:113], v[102:103], off
	global_load_dwordx2 v[114:115], v[102:103], off offset:512
	global_load_dwordx2 v[116:117], v[102:103], off offset:1024
	global_load_dwordx2 v[118:119], v[102:103], off offset:1536
	v_cndmask_b32_e32 v87, v87, v91, vcc
	v_cndmask_b32_e32 v86, v86, v90, vcc
	v_cndmask_b32_e32 v89, v89, v105, vcc
	v_cndmask_b32_e32 v88, v88, v104, vcc
	v_lshl_add_u64 v[90:91], v[86:87], 0, v[180:181]
	v_lshl_add_u64 v[92:93], v[82:83], 0, v[100:101]
	v_lshl_add_u64 v[120:121], v[88:89], 0, v[180:181]
	global_load_dwordx4 v[86:89], v[90:91], off nt
	global_load_dwordx4 v[100:103], v[90:91], off offset:1024 nt
	global_load_dwordx4 v[104:107], v[90:91], off offset:2048 nt
	global_load_dwordx4 v[108:111], v[90:91], off offset:3072 nt
	v_add_u32_e32 v84, s45, v84
	v_cmp_lt_i32_e32 vcc, s46, v84
	s_or_b64 s[8:9], vcc, s[8:9]
	s_waitcnt vmcnt(7)
	v_lshlrev_b32_e32 v90, 16, v112
	v_and_b32_e32 v91, 0xffff0000, v112
	s_waitcnt vmcnt(6)
	v_lshlrev_b32_e32 v122, 16, v114
	v_and_b32_e32 v123, 0xffff0000, v114
	v_lshlrev_b32_e32 v112, 16, v113
	v_and_b32_e32 v113, 0xffff0000, v113
	v_lshlrev_b32_e32 v114, 16, v115
	v_and_b32_e32 v115, 0xffff0000, v115
	s_waitcnt vmcnt(5)
	v_lshlrev_b32_e32 v124, 16, v116
	v_and_b32_e32 v125, 0xffff0000, v116
	v_lshlrev_b32_e32 v116, 16, v117
	v_and_b32_e32 v117, 0xffff0000, v117
	s_waitcnt vmcnt(4)
	v_lshlrev_b32_e32 v126, 16, v118
	v_and_b32_e32 v127, 0xffff0000, v118
	v_lshlrev_b32_e32 v118, 16, v119
	v_and_b32_e32 v119, 0xffff0000, v119
	v_pk_mul_f32 v[90:91], v[32:33], v[90:91]
	v_pk_mul_f32 v[122:123], v[40:41], v[122:123]
	v_pk_mul_f32 v[112:113], v[34:35], v[112:113]
	v_pk_mul_f32 v[114:115], v[42:43], v[114:115]
	v_pk_mul_f32 v[116:117], v[50:51], v[116:117]
	v_pk_mul_f32 v[118:119], v[58:59], v[118:119]
	s_waitcnt vmcnt(3)
	v_pk_fma_f32 v[86:87], v[86:87], s[44:45], v[90:91] op_sel_hi:[1,0,1]
	s_waitcnt vmcnt(2)
	v_pk_fma_f32 v[100:101], v[100:101], s[44:45], v[122:123] op_sel_hi:[1,0,1]
	v_pk_mul_f32 v[124:125], v[48:49], v[124:125]
	v_pk_mul_f32 v[126:127], v[56:57], v[126:127]
	v_pk_fma_f32 v[88:89], v[88:89], s[44:45], v[112:113] op_sel_hi:[1,0,1]
	v_pk_fma_f32 v[90:91], v[102:103], s[44:45], v[114:115] op_sel_hi:[1,0,1]
	s_waitcnt vmcnt(1)
	v_pk_fma_f32 v[102:103], v[106:107], s[44:45], v[116:117] op_sel_hi:[1,0,1]
	s_waitcnt vmcnt(0)
	v_pk_fma_f32 v[106:107], v[110:111], s[44:45], v[118:119] op_sel_hi:[1,0,1]
	v_mov_b32_e32 v110, v86
	v_mov_b32_e32 v111, v100
	v_mov_b32_e32 v112, v87
	v_mov_b32_e32 v113, v101
	v_pk_fma_f32 v[104:105], v[104:105], s[44:45], v[124:125] op_sel_hi:[1,0,1]
	v_pk_fma_f32 v[108:109], v[108:109], s[44:45], v[126:127] op_sel_hi:[1,0,1]
	v_mov_b32_e32 v114, v88
	v_mov_b32_e32 v115, v90
	v_pk_add_f32 v[110:111], v[110:111], v[112:113]
	v_mov_b32_e32 v116, v89
	v_mov_b32_e32 v117, v91
	v_mov_b32_e32 v118, v104
	v_mov_b32_e32 v119, v108
	v_mov_b32_e32 v122, v105
	v_mov_b32_e32 v123, v109
	v_pk_add_f32 v[110:111], v[114:115], v[110:111]
	v_mov_b32_e32 v124, v102
	v_mov_b32_e32 v125, v106
	v_pk_add_f32 v[112:113], v[118:119], v[122:123]
	v_pk_add_f32 v[110:111], v[116:117], v[110:111]
	v_mov_b32_e32 v126, v103
	v_mov_b32_e32 v127, v107
	v_pk_add_f32 v[112:113], v[124:125], v[112:113]
	v_add_f32_e32 v85, 0, v110
	v_pk_add_f32 v[112:113], v[126:127], v[112:113]
	v_add_f32_e32 v85, v85, v111
	v_add_f32_e32 v85, v85, v112
	v_add_f32_e32 v85, v85, v113
	v_mov_b32_e32 v110, v85
	v_mov_b32_e32 v212, v85
	s_mov_b32 s100, 0
	s_mov_b32 s101, -1
	v_permlane32_swap_b32_e32 v110, v212
	v_cndmask_b32_e64 v110, v212, v110, s[100:101]
	s_waitcnt lgkmcnt(0)
	v_add_f32_e32 v85, v85, v110
	v_mov_b32_e32 v110, v85
	v_mov_b32_e32 v212, v85
	s_mov_b32 s100, 0xffff0000
	s_mov_b32 s101, 0xffff0000
	v_permlane16_swap_b32_e32 v110, v212
	v_cndmask_b32_e64 v110, v212, v110, s[100:101]
	s_waitcnt lgkmcnt(0)
	v_add_f32_e32 v85, v85, v110
	s_nop 1
	v_mov_b32_dpp v110, v85 row_ror:8 row_mask:0xf bank_mask:0xf
	s_waitcnt lgkmcnt(0)
	v_add_f32_e32 v85, v85, v110
	s_nop 1
	v_mov_b32_dpp v110, v85 row_ror:4 row_mask:0xf bank_mask:0xf
	s_waitcnt lgkmcnt(0)
	v_add_f32_e32 v85, v85, v110
	s_nop 1
	v_mov_b32_dpp v110, v85 quad_perm:[2,3,0,1] row_mask:0xf bank_mask:0xf
	s_waitcnt lgkmcnt(0)
	v_add_f32_e32 v85, v85, v110
	s_nop 1
	v_mov_b32_dpp v110, v85 quad_perm:[1,0,3,2] row_mask:0xf bank_mask:0xf
	s_waitcnt lgkmcnt(0)
; DI unsigned cvt_pk_bf16(float lo, float hi) { unsigned r; asm volatile("v_cvt_pk_bf16_f32 %0, %1, %2" : "=v"(r) : "v"(lo), "v"(hi)); return r; }
; template <int NR>
; DI void ln_rows(const Args& a, int l, int row0, int lane, const f32x4 (&lgv)[4], const f32x4 (&lbv)[4], const f32x4 (&gate)[4], const f32x4 (&sh)[4], const f32x4 (&sc1)[4]) {
;     ...
;     for (int k = 0; k < NR; ++k) { float q = 0.f;
; #pragma unroll
;         for (int i = 0; i < 4; ++i) { v[k][i] = v[k][i] - mean[k]; q += v[k][i][0] * v[k][i][0] + v[k][i][1] * v[k][i][1] + v[k][i][2] * v[k][i][2] + v[k][i][3] * v[k][i][3]; }
;         rstd[k] = rsqrtf(wave_sum(q) * (1.f / 1024.f) + 1e-5f); }
; #pragma unroll
;     for (int k = 0; k < NR; ++k) { const int row = row0 + k;
;         float* zr = row < TL ? a.out + (size_t)row * 1024 : zc + (size_t)(row - TL) * 1024;
; #pragma unroll
;         for (int i = 0; i < 4; ++i) { const int col = 4 * lane + 256 * i;
;             const f32x4 yo = v[k][i] * rstd[k] * lgv[i] + lbv[i];
;             *(f32x4*)(zr + col) = yo;
;             if (l < 3) { const f32x4 hv = yo * sc1[i] + sh[i]; u32x2 w = {cvt_pk_bf16(hv[0], hv[1]), cvt_pk_bf16(hv[2], hv[3])}; *(u32x2*)(h + (size_t)row * 1024 + col) = w; } } }
	v_add_f32_e32 v85, v85, v110
	v_fmamk_f32 v87, v85, 0xba800000, v87
	v_fmamk_f32 v101, v85, 0xba800000, v101
	v_fmac_f32_e32 v86, 0xba800000, v85
	v_fmac_f32_e32 v100, 0xba800000, v85
	v_fmamk_f32 v105, v85, 0xba800000, v105
	v_fmamk_f32 v109, v85, 0xba800000, v109
	v_mov_b32_e32 v112, v87
	v_mov_b32_e32 v113, v101
	v_fmac_f32_e32 v88, 0xba800000, v85
	v_fmac_f32_e32 v90, 0xba800000, v85
	v_fmac_f32_e32 v104, 0xba800000, v85
	v_fmac_f32_e32 v108, 0xba800000, v85
	v_mov_b32_e32 v110, v86
	v_mov_b32_e32 v111, v100
	v_mov_b32_e32 v122, v109
	v_mov_b32_e32 v123, v105
	v_pk_mul_f32 v[112:113], v[112:113], v[112:113]
	v_fmamk_f32 v89, v85, 0xba800000, v89
	v_fmamk_f32 v91, v85, 0xba800000, v91
	v_fmac_f32_e32 v102, 0xba800000, v85
	v_fmac_f32_e32 v106, 0xba800000, v85
	v_mov_b32_e32 v114, v88
	v_mov_b32_e32 v115, v90
	v_mov_b32_e32 v118, v108
	v_mov_b32_e32 v119, v104
	v_pk_mul_f32 v[122:123], v[122:123], v[122:123]
	v_pk_fma_f32 v[110:111], v[110:111], v[110:111], v[112:113]
	v_fmamk_f32 v103, v85, 0xba800000, v103
	v_fmamk_f32 v107, v85, 0xba800000, v107
	v_mov_b32_e32 v116, v89
	v_mov_b32_e32 v117, v91
	v_mov_b32_e32 v124, v106
	v_mov_b32_e32 v125, v102
	v_pk_fma_f32 v[112:113], v[118:119], v[118:119], v[122:123]
	v_pk_fma_f32 v[110:111], v[114:115], v[114:115], v[110:111]
	v_mov_b32_e32 v126, v107
	v_mov_b32_e32 v127, v103
	v_pk_fma_f32 v[112:113], v[124:125], v[124:125], v[112:113]
	v_pk_fma_f32 v[110:111], v[116:117], v[116:117], v[110:111]
	v_pk_fma_f32 v[112:113], v[126:127], v[126:127], v[112:113]
	v_add_f32_e32 v85, v110, v111
	v_add_f32_e32 v85, v113, v85
	v_add_f32_e32 v85, v112, v85
	v_mov_b32_e32 v110, v85
	v_mov_b32_e32 v212, v85
	s_mov_b32 s100, 0
	s_mov_b32 s101, -1
	v_permlane32_swap_b32_e32 v110, v212
	v_cndmask_b32_e64 v110, v212, v110, s[100:101]
	s_waitcnt lgkmcnt(0)
	v_add_f32_e32 v85, v85, v110
	v_mov_b32_e32 v110, v85
	v_mov_b32_e32 v212, v85
	s_mov_b32 s100, 0xffff0000
	s_mov_b32 s101, 0xffff0000
	v_permlane16_swap_b32_e32 v110, v212
	v_cndmask_b32_e64 v110, v212, v110, s[100:101]
	s_waitcnt lgkmcnt(0)
	v_add_f32_e32 v85, v85, v110
	s_nop 1
	v_mov_b32_dpp v110, v85 row_ror:8 row_mask:0xf bank_mask:0xf
	s_waitcnt lgkmcnt(0)
	v_add_f32_e32 v85, v85, v110
	s_nop 1
	v_mov_b32_dpp v110, v85 row_ror:4 row_mask:0xf bank_mask:0xf
	s_waitcnt lgkmcnt(0)
	v_add_f32_e32 v85, v85, v110
	s_nop 1
	v_mov_b32_dpp v110, v85 quad_perm:[2,3,0,1] row_mask:0xf bank_mask:0xf
	s_waitcnt lgkmcnt(0)
	v_add_f32_e32 v85, v85, v110
	s_nop 1
	v_mov_b32_dpp v110, v85 quad_perm:[1,0,3,2] row_mask:0xf bank_mask:0xf
	s_waitcnt lgkmcnt(0)
	v_add_f32_e32 v85, v85, v110
	v_fmamk_f32 v85, v85, 0x3a800000, v182
	v_mul_f32_e32 v110, 0x4b800000, v85
	v_cmp_gt_f32_e32 vcc, s94, v85
	s_nop 1
	v_cndmask_b32_e32 v85, v85, v110, vcc
	v_rsq_f32_e32 v85, v85
	s_nop 0
	v_mul_f32_e32 v110, 0x45800000, v85
	v_cndmask_b32_e32 v110, v85, v110, vcc
	v_pk_mul_f32 v[86:87], v[86:87], v[110:111] op_sel_hi:[1,0]
	v_pk_mul_f32 v[88:89], v[88:89], v[110:111] op_sel_hi:[1,0]
	v_pk_fma_f32 v[86:87], v[0:1], v[86:87], v[8:9]
	v_pk_fma_f32 v[88:89], v[2:3], v[88:89], v[10:11]
	v_pk_mul_f32 v[100:101], v[100:101], v[110:111] op_sel_hi:[1,0]
	v_pk_mul_f32 v[90:91], v[90:91], v[110:111] op_sel_hi:[1,0]
	global_store_dwordx4 v[120:121], v[86:89], off nt
	v_pk_mul_f32 v[104:105], v[104:105], v[110:111] op_sel_hi:[1,0]
	v_pk_mul_f32 v[112:113], v[102:103], v[110:111] op_sel_hi:[1,0]
	v_pk_fma_f32 v[86:87], v[66:67], v[86:87], v[36:37]
	v_pk_fma_f32 v[102:103], v[6:7], v[90:91], v[14:15]
	v_pk_fma_f32 v[100:101], v[4:5], v[100:101], v[12:13]
	v_pk_fma_f32 v[88:89], v[64:65], v[88:89], v[38:39]
	v_cvt_pk_bf16_f32 v86, v86, v87
	v_pk_mul_f32 v[108:109], v[108:109], v[110:111] op_sel_hi:[1,0]
	v_cvt_pk_bf16_f32 v87, v88, v89
	v_pk_mul_f32 v[110:111], v[106:107], v[110:111] op_sel_hi:[1,0]
	v_pk_fma_f32 v[106:107], v[18:19], v[112:113], v[26:27]
	v_pk_fma_f32 v[104:105], v[16:17], v[104:105], v[24:25]
	v_pk_fma_f32 v[90:91], v[68:69], v[102:103], v[46:47]
	v_pk_fma_f32 v[112:113], v[70:71], v[100:101], v[44:45]
	global_store_dwordx2 v[92:93], v[86:87], off
	global_store_dwordx4 v[120:121], v[100:103], off offset:1024 nt
	v_cvt_pk_bf16_f32 v86, v112, v113
	v_cvt_pk_bf16_f32 v87, v90, v91
	v_pk_fma_f32 v[110:111], v[22:23], v[110:111], v[30:31]
	v_pk_fma_f32 v[108:109], v[20:21], v[108:109], v[28:29]
	v_pk_fma_f32 v[114:115], v[72:73], v[106:107], v[54:55]
	v_pk_fma_f32 v[116:117], v[74:75], v[104:105], v[52:53]
	global_store_dwordx2 v[92:93], v[86:87], off offset:512
	global_store_dwordx4 v[120:121], v[104:107], off offset:2048 nt
	v_cvt_pk_bf16_f32 v86, v116, v117
	v_cvt_pk_bf16_f32 v87, v114, v115
	v_pk_fma_f32 v[118:119], v[76:77], v[110:111], v[62:63]
	v_pk_fma_f32 v[122:123], v[78:79], v[108:109], v[60:61]
	global_store_dwordx2 v[92:93], v[86:87], off offset:1024
	global_store_dwordx4 v[120:121], v[108:111], off offset:3072 nt
	v_cvt_pk_bf16_f32 v86, v122, v123
	v_cvt_pk_bf16_f32 v87, v118, v119
	global_store_dwordx2 v[92:93], v[86:87], off offset:1536
	s_andn2_b64 exec, exec, s[8:9]
	s_cbranch_execnz .LBB0_1010
